# P9 conv epilogue: second-half (n=1) weight loads issued at the top with the first half's, no mid-epilogue wait ladder
# speedup vs baseline: 1.0007x; 1.0007x over previous
; __device__ __forceinline__ void st_bf4(bf16_t* p, f32x4 v) { u32x2 w; w.x = pk2(v[0], v[1]); w.y = pk2(v[2], v[3]); *(u32x2*)p = w; }
; __device__ __forceinline__ float sigmoidf_(float x) { return __builtin_amdgcn_rcpf(1.f + __expf(-x)); }
; __device__ __forceinline__ float dpp_ror1(float v) { return __int_as_float(__builtin_amdgcn_update_dpp(0, __float_as_int(v), 0x121, 0xf, 0xf, false)); }
; __device__ __forceinline__ float dpp_rol1(float v) { return __int_as_float(__builtin_amdgcn_update_dpp(0, __float_as_int(v), 0x12F, 0xf, 0xf, false)); }
;     __device__ __forceinline__ void tile(const f32x4 (&acc)[2][2][4][2], const Unit& u, int wr, int wc, int fr, int fq) const {
; #pragma unroll
;         for (int n = 0; n < 2; ++n) {
;             const int cv = 128 * u.pn + 32 * wc + 16 * n + 4 * fq, cg = FF + cv;
;             const f32x4 wv0 = *(const f32x4*)(cw + cv), wv1 = *(const f32x4*)(cw + F2 + cv), wv2 = *(const f32x4*)(cw + 2 * F2 + cv), bv = *(const f32x4*)(cb + cv);
;             const f32x4 wg0 = *(const f32x4*)(cw + cg), wg1 = *(const f32x4*)(cw + F2 + cg), wg2 = *(const f32x4*)(cw + 2 * F2 + cg), bg = *(const f32x4*)(cb + cg);
; #pragma unroll
;             for (int ai = 0; ai < 2; ++ai)
; #pragma unroll
;                 for (int m = 0; m < 4; ++m) {
;                     f32x4 r;
; #pragma unroll
;                     for (int i = 0; i < 4; ++i) {
;                         const float xv = acc[ai][0][m][n][i], xg = acc[ai][1][m][n][i];
;                         const float uv = m > 0 ? acc[ai][0][m > 0 ? m - 1 : 0][n][i] : 0.f, ug = m > 0 ? acc[ai][1][m > 0 ? m - 1 : 0][n][i] : 0.f;
;                         const float dv = m < 3 ? acc[ai][0][m < 3 ? m + 1 : 3][n][i] : 0.f, dg = m < 3 ? acc[ai][1][m < 3 ? m + 1 : 3][n][i] : 0.f;
;                         const float pv = dpp_ror1(fr == 15 ? uv : xv), pg = dpp_ror1(fr == 15 ? ug : xg);
;                         const float nv = dpp_rol1(fr == 0 ? dv : xv), ng = dpp_rol1(fr == 0 ? dg : xg);
;                         const float yv = wv0[i] * pv + wv1[i] * xv + wv2[i] * nv + bv[i];
;                         const float yg = wg0[i] * pg + wg1[i] * xg + wg2[i] * ng + bg[i];
;                         r[i] = yg * sigmoidf_(yg) * yv;
;                     }
;                     st_bf4(ACT + (size_t)(u.pm * BM + ai * HALF + wr * 64 + m * 16 + fr) * FF + cv, r);
.LBB0_1802:
	v_lshl_or_b32 v170, s33, 7, v204
	v_ashrrev_i32_e32 v171, 31, v170
	v_lshlrev_b64 v[120:121], 2, v[170:171]
	v_lshl_add_u64 v[172:173], s[56:57], 0, v[120:121]
	v_add_co_u32_e32 v176, vcc, 0x5000, v172
	v_lshl_add_u64 v[122:123], s[12:13], 0, v[120:121]
	s_nop 0
	v_addc_co_u32_e32 v177, vcc, 0, v173, vcc
	v_add_co_u32_e32 v178, vcc, 0x5000, v122
	v_lshl_add_u64 v[124:125], s[14:15], 0, v[120:121]
	s_nop 0
	v_addc_co_u32_e32 v179, vcc, 0, v123, vcc
	global_load_dwordx4 v[132:135], v[176:177], off offset:2048
	global_load_dwordx4 v[148:151], v[178:179], off offset:2048
	v_add_co_u32_e32 v180, vcc, 0x5000, v124
	v_lshl_add_u64 v[174:175], s[58:59], 0, v[120:121]
	s_nop 0
	v_addc_co_u32_e32 v181, vcc, 0, v125, vcc
	global_load_dwordx4 v[136:139], v[180:181], off offset:2048
	v_add_co_u32_e32 v182, vcc, 0x5000, v174
	v_cndmask_b32_e64 v168, v156, 0, s[4:5]
	s_nop 0
	v_addc_co_u32_e32 v183, vcc, 0, v175, vcc
	global_load_dwordx4 v[140:143], v[182:183], off offset:2048
	global_load_dwordx4 v[230:233], v[176:177], off offset:2112
	global_load_dwordx4 v[234:237], v[178:179], off offset:2112
	global_load_dwordx4 v[238:241], v[180:181], off offset:2112
	global_load_dwordx4 v[242:245], v[182:183], off offset:2112
	global_load_dwordx4 v[246:249], v[122:123], off offset:64
	global_load_dwordx4 v[144:147], v[122:123], off
	s_nop 0
	global_load_dwordx4 v[250:253], v[172:173], off offset:64
	global_load_dwordx4 v[120:123], v[172:173], off
	s_nop 0
	global_load_dwordx4 v[190:193], v[124:125], off offset:64
	global_load_dwordx4 v[124:127], v[124:125], off
	s_nop 0
	global_load_dwordx4 v[128:131], v[174:175], off
	s_nop 0
	global_load_dwordx4 v[180:183], v[174:175], off offset:64
	v_cndmask_b32_e64 v169, v152, 0, s[4:5]
	v_mov_b32_dpp v208, v168 row_ror:1 row_mask:0xf bank_mask:0xf
	s_nop 0
	v_mov_b32_dpp v168, v169 row_ror:1 row_mask:0xf bank_mask:0xf
	v_cndmask_b32_e64 v169, v156, v116, s[6:7]
	v_cndmask_b32_e64 v184, v153, 0, s[4:5]
	s_nop 0
	v_mov_b32_dpp v210, v169 row_ror:15 row_mask:0xf bank_mask:0xf
	v_cndmask_b32_e64 v169, v152, v112, s[6:7]
	s_nop 1
	v_mov_b32_dpp v186, v169 row_ror:15 row_mask:0xf bank_mask:0xf
	v_cndmask_b32_e64 v169, v157, 0, s[4:5]
	s_nop 1
	v_mov_b32_dpp v209, v169 row_ror:1 row_mask:0xf bank_mask:0xf
	v_mov_b32_dpp v169, v184 row_ror:1 row_mask:0xf bank_mask:0xf
	v_cndmask_b32_e64 v184, v157, v117, s[6:7]
	s_nop 1
	v_mov_b32_dpp v211, v184 row_ror:15 row_mask:0xf bank_mask:0xf
	v_cndmask_b32_e64 v184, v153, v113, s[6:7]
	s_lshl_b32 s17, s26, 8
	s_nop 0
	v_mov_b32_dpp v187, v184 row_ror:15 row_mask:0xf bank_mask:0xf
	v_cndmask_b32_e64 v184, v158, 0, s[4:5]
	v_add_u32_e32 v220, s17, v195
	s_andn2_b64 vcc, exec, s[20:21]
	v_mov_b32_dpp v212, v184 row_ror:1 row_mask:0xf bank_mask:0xf
	v_cndmask_b32_e64 v184, v154, 0, s[4:5]
	s_mov_b64 s[20:21], -1
	s_waitcnt vmcnt(0)
	v_pk_mul_f32 v[222:223], v[152:153], v[148:149]
	s_nop 0
	v_pk_fma_f32 v[168:169], v[132:133], v[168:169], v[222:223]
	v_mov_b32_dpp v214, v184 row_ror:1 row_mask:0xf bank_mask:0xf
	v_cndmask_b32_e64 v184, v158, v118, s[6:7]
	v_pk_fma_f32 v[168:169], v[136:137], v[186:187], v[168:169]
	v_lshlrev_b64 v[186:187], 1, v[170:171]
	v_pk_add_f32 v[222:223], v[140:141], v[168:169]
	v_mov_b32_dpp v216, v184 row_ror:15 row_mask:0xf bank_mask:0xf
	v_mul_f32_e32 v168, 0xbfb8aa3b, v222
	v_exp_f32_e32 v224, v168
	v_cndmask_b32_e64 v184, v154, v114, s[6:7]
	v_pk_mul_f32 v[228:229], v[156:157], v[144:145]
	v_pk_mul_f32 v[226:227], v[158:159], v[146:147]
	v_add_f32_e32 v171, 1.0, v224
	v_mul_f32_e32 v224, 0xbfb8aa3b, v223
	v_exp_f32_e32 v225, v224
	v_mov_b32_dpp v218, v184 row_ror:15 row_mask:0xf bank_mask:0xf
	v_cndmask_b32_e64 v184, v159, 0, s[4:5]
	v_rcp_f32_e32 v224, v171
	v_add_f32_e32 v171, 1.0, v225
	v_mov_b32_dpp v213, v184 row_ror:1 row_mask:0xf bank_mask:0xf
	v_cndmask_b32_e64 v184, v155, 0, s[4:5]
	v_rcp_f32_e32 v225, v171
	v_pk_fma_f32 v[208:209], v[120:121], v[208:209], v[228:229]
	v_mov_b32_dpp v215, v184 row_ror:1 row_mask:0xf bank_mask:0xf
	v_cndmask_b32_e64 v184, v159, v119, s[6:7]
	v_pk_fma_f32 v[208:209], v[124:125], v[210:211], v[208:209]
	v_pk_mul_f32 v[210:211], v[222:223], v[224:225]
	v_mov_b32_dpp v217, v184 row_ror:15 row_mask:0xf bank_mask:0xf
	v_cndmask_b32_e64 v184, v155, v115, s[6:7]
	v_pk_add_f32 v[208:209], v[128:129], v[208:209]
	v_pk_fma_f32 v[212:213], v[122:123], v[212:213], v[226:227]
	v_mov_b32_dpp v219, v184 row_ror:15 row_mask:0xf bank_mask:0xf
	v_mov_b64_e32 v[184:185], s[0:1]
	v_mad_i64_i32 v[220:221], s[28:29], v220, s46, v[184:185]
	v_lshl_add_u64 v[168:169], v[220:221], 0, v[186:187]
	v_pk_mul_f32 v[220:221], v[154:155], v[150:151]
	v_pk_mul_f32 v[208:209], v[208:209], v[210:211]
	v_pk_fma_f32 v[210:211], v[134:135], v[214:215], v[220:221]
	v_pk_fma_f32 v[212:213], v[126:127], v[216:217], v[212:213]
	v_pk_fma_f32 v[210:211], v[138:139], v[218:219], v[210:211]
	v_pk_add_f32 v[212:213], v[130:131], v[212:213]
	v_pk_add_f32 v[210:211], v[142:143], v[210:211]
	v_cvt_pk_bf16_f32 v208, v208, v209
	v_mul_f32_e32 v171, 0xbfb8aa3b, v210
	v_exp_f32_e32 v171, v171
	v_mul_f32_e32 v214, 0xbfb8aa3b, v211
	v_exp_f32_e32 v215, v214
	v_pk_mul_f32 v[216:217], v[112:113], v[148:149]
	v_add_f32_e32 v171, 1.0, v171
	v_rcp_f32_e32 v214, v171
	v_add_f32_e32 v171, 1.0, v215
	v_rcp_f32_e32 v215, v171
	v_cndmask_b32_e64 v171, v116, v156, s[4:5]
	v_pk_mul_f32 v[222:223], v[116:117], v[144:145]
	v_pk_mul_f32 v[210:211], v[210:211], v[214:215]
	v_mov_b32_dpp v156, v171 row_ror:1 row_mask:0xf bank_mask:0xf
	v_pk_mul_f32 v[210:211], v[212:213], v[210:211]
	v_cndmask_b32_e64 v171, v112, v152, s[4:5]
	v_cvt_pk_bf16_f32 v209, v210, v211
; __device__ __forceinline__ void st_bf4(bf16_t* p, f32x4 v) { u32x2 w; w.x = pk2(v[0], v[1]); w.y = pk2(v[2], v[3]); *(u32x2*)p = w; }
; __device__ __forceinline__ float sigmoidf_(float x) { return __builtin_amdgcn_rcpf(1.f + __expf(-x)); }
; __device__ __forceinline__ float dpp_ror1(float v) { return __int_as_float(__builtin_amdgcn_update_dpp(0, __float_as_int(v), 0x121, 0xf, 0xf, false)); }
; __device__ __forceinline__ float dpp_rol1(float v) { return __int_as_float(__builtin_amdgcn_update_dpp(0, __float_as_int(v), 0x12F, 0xf, 0xf, false)); }
;     __device__ __forceinline__ void tile(const f32x4 (&acc)[2][2][4][2], const Unit& u, int wr, int wc, int fr, int fq) const {
;     ...
;                     for (int i = 0; i < 4; ++i) {
;                         const float xv = acc[ai][0][m][n][i], xg = acc[ai][1][m][n][i];
;                         const float uv = m > 0 ? acc[ai][0][m > 0 ? m - 1 : 0][n][i] : 0.f, ug = m > 0 ? acc[ai][1][m > 0 ? m - 1 : 0][n][i] : 0.f;
;                         const float dv = m < 3 ? acc[ai][0][m < 3 ? m + 1 : 3][n][i] : 0.f, dg = m < 3 ? acc[ai][1][m < 3 ? m + 1 : 3][n][i] : 0.f;
;                         const float pv = dpp_ror1(fr == 15 ? uv : xv), pg = dpp_ror1(fr == 15 ? ug : xg);
;                         const float nv = dpp_rol1(fr == 0 ? dv : xv), ng = dpp_rol1(fr == 0 ? dg : xg);
;                         const float yv = wv0[i] * pv + wv1[i] * xv + wv2[i] * nv + bv[i];
;                         const float yg = wg0[i] * pg + wg1[i] * xg + wg2[i] * ng + bg[i];
;                         r[i] = yg * sigmoidf_(yg) * yv;
;                     }
;                     st_bf4(ACT + (size_t)(u.pm * BM + ai * HALF + wr * 64 + m * 16 + fr) * FF + cv, r);
	global_store_dwordx2 v[168:169], v[208:209], off
	v_mov_b32_dpp v152, v171 row_ror:1 row_mask:0xf bank_mask:0xf
	v_cndmask_b32_e64 v171, v116, v108, s[6:7]
	s_nop 1
	v_mov_b32_dpp v208, v171 row_ror:15 row_mask:0xf bank_mask:0xf
	v_cndmask_b32_e64 v171, v112, v104, s[6:7]
	s_nop 1
	v_mov_b32_dpp v210, v171 row_ror:15 row_mask:0xf bank_mask:0xf
	v_cndmask_b32_e64 v171, v117, v157, s[4:5]
	s_nop 1
	v_mov_b32_dpp v157, v171 row_ror:1 row_mask:0xf bank_mask:0xf
	v_cndmask_b32_e64 v171, v113, v153, s[4:5]
	v_pk_fma_f32 v[156:157], v[120:121], v[156:157], v[222:223]
	s_nop 0
	v_mov_b32_dpp v153, v171 row_ror:1 row_mask:0xf bank_mask:0xf
	v_cndmask_b32_e64 v171, v117, v109, s[6:7]
	v_pk_fma_f32 v[152:153], v[132:133], v[152:153], v[216:217]
	v_pk_mul_f32 v[216:217], v[114:115], v[150:151]
	v_mov_b32_dpp v209, v171 row_ror:15 row_mask:0xf bank_mask:0xf
	v_cndmask_b32_e64 v171, v113, v105, s[6:7]
	v_pk_fma_f32 v[156:157], v[124:125], v[208:209], v[156:157]
	v_pk_mul_f32 v[220:221], v[118:119], v[146:147]
	v_mov_b32_dpp v211, v171 row_ror:15 row_mask:0xf bank_mask:0xf
	v_cndmask_b32_e64 v171, v118, v158, s[4:5]
	v_pk_fma_f32 v[152:153], v[136:137], v[210:211], v[152:153]
	v_pk_add_f32 v[156:157], v[128:129], v[156:157]
	v_mov_b32_dpp v158, v171 row_ror:1 row_mask:0xf bank_mask:0xf
	v_cndmask_b32_e64 v171, v114, v154, s[4:5]
	v_pk_add_f32 v[210:211], v[140:141], v[152:153]
	s_nop 0
	v_mov_b32_dpp v154, v171 row_ror:1 row_mask:0xf bank_mask:0xf
	v_cndmask_b32_e64 v171, v118, v110, s[6:7]
	v_mul_f32_e32 v152, 0xbfb8aa3b, v210
	v_exp_f32_e32 v218, v152
	v_mov_b32_dpp v212, v171 row_ror:15 row_mask:0xf bank_mask:0xf
	v_cndmask_b32_e64 v171, v114, v106, s[6:7]
	s_nop 1
	v_mov_b32_dpp v214, v171 row_ror:15 row_mask:0xf bank_mask:0xf
	v_cndmask_b32_e64 v171, v119, v159, s[4:5]
	s_nop 1
	v_mov_b32_dpp v159, v171 row_ror:1 row_mask:0xf bank_mask:0xf
	v_cndmask_b32_e64 v171, v115, v155, s[4:5]
	v_pk_fma_f32 v[158:159], v[122:123], v[158:159], v[220:221]
	s_nop 0
	v_mov_b32_dpp v155, v171 row_ror:1 row_mask:0xf bank_mask:0xf
	v_cndmask_b32_e64 v171, v119, v111, s[6:7]
	v_pk_fma_f32 v[154:155], v[134:135], v[154:155], v[216:217]
	v_pk_mul_f32 v[216:217], v[108:109], v[144:145]
	v_mov_b32_dpp v213, v171 row_ror:15 row_mask:0xf bank_mask:0xf
	v_cndmask_b32_e64 v171, v115, v107, s[6:7]
	v_pk_fma_f32 v[158:159], v[126:127], v[212:213], v[158:159]
	s_nop 0
	v_mov_b32_dpp v215, v171 row_ror:15 row_mask:0xf bank_mask:0xf
	v_add_u32_e32 v171, s17, v197
	v_mad_i64_i32 v[152:153], s[28:29], v171, s46, v[184:185]
	v_add_f32_e32 v171, 1.0, v218
	v_mul_f32_e32 v218, 0xbfb8aa3b, v211
	v_exp_f32_e32 v219, v218
	v_rcp_f32_e32 v218, v171
	v_pk_fma_f32 v[154:155], v[138:139], v[214:215], v[154:155]
	v_pk_add_f32 v[158:159], v[130:131], v[158:159]
	v_add_f32_e32 v171, 1.0, v219
	v_rcp_f32_e32 v219, v171
	v_pk_add_f32 v[154:155], v[142:143], v[154:155]
	v_lshl_add_u64 v[152:153], v[152:153], 0, v[186:187]
	v_mul_f32_e32 v171, 0xbfb8aa3b, v154
	v_pk_mul_f32 v[208:209], v[210:211], v[218:219]
	v_exp_f32_e32 v171, v171
	v_pk_mul_f32 v[156:157], v[156:157], v[208:209]
	v_mul_f32_e32 v208, 0xbfb8aa3b, v155
	v_exp_f32_e32 v209, v208
	v_cvt_pk_bf16_f32 v156, v156, v157
	v_add_f32_e32 v157, 1.0, v171
	v_rcp_f32_e32 v208, v157
	v_add_f32_e32 v157, 1.0, v209
	v_rcp_f32_e32 v209, v157
	v_pk_mul_f32 v[210:211], v[104:105], v[148:149]
	v_cndmask_b32_e64 v171, v111, v103, s[6:7]
	v_pk_mul_f32 v[214:215], v[110:111], v[146:147]
	v_pk_mul_f32 v[154:155], v[154:155], v[208:209]
	s_nop 0
	v_pk_mul_f32 v[154:155], v[158:159], v[154:155]
	v_cndmask_b32_e64 v158, v105, v97, s[6:7]
	v_cvt_pk_bf16_f32 v157, v154, v155
	v_cndmask_b32_e64 v154, v108, v116, s[4:5]
	v_cndmask_b32_e64 v155, v108, v100, s[6:7]
	global_store_dwordx2 v[152:153], v[156:157], off
	v_mov_b32_dpp v116, v154 row_ror:1 row_mask:0xf bank_mask:0xf
	v_cndmask_b32_e64 v154, v104, v112, s[4:5]
	v_cndmask_b32_e64 v157, v109, v101, s[6:7]
	s_nop 0
	v_mov_b32_dpp v112, v154 row_ror:1 row_mask:0xf bank_mask:0xf
	v_cndmask_b32_e64 v159, v110, v102, s[6:7]
	v_mov_b32_dpp v154, v155 row_ror:15 row_mask:0xf bank_mask:0xf
	v_cndmask_b32_e64 v155, v104, v96, s[6:7]
	s_nop 1
	v_mov_b32_dpp v156, v155 row_ror:15 row_mask:0xf bank_mask:0xf
	v_cndmask_b32_e64 v155, v109, v117, s[4:5]
	s_nop 1
	v_mov_b32_dpp v117, v155 row_ror:1 row_mask:0xf bank_mask:0xf
	v_cndmask_b32_e64 v155, v105, v113, s[4:5]
	v_pk_fma_f32 v[116:117], v[120:121], v[116:117], v[216:217]
	s_nop 0
	v_mov_b32_dpp v113, v155 row_ror:1 row_mask:0xf bank_mask:0xf
	v_pk_fma_f32 v[112:113], v[132:133], v[112:113], v[210:211]
	v_pk_mul_f32 v[210:211], v[106:107], v[150:151]
	v_mov_b32_dpp v155, v157 row_ror:15 row_mask:0xf bank_mask:0xf
	v_pk_fma_f32 v[116:117], v[124:125], v[154:155], v[116:117]
	s_nop 0
	v_mov_b32_dpp v157, v158 row_ror:15 row_mask:0xf bank_mask:0xf
	v_cndmask_b32_e64 v158, v110, v118, s[4:5]
	v_pk_fma_f32 v[112:113], v[136:137], v[156:157], v[112:113]
	v_pk_add_f32 v[116:117], v[128:129], v[116:117]
	v_mov_b32_dpp v118, v158 row_ror:1 row_mask:0xf bank_mask:0xf
	v_cndmask_b32_e64 v158, v106, v114, s[4:5]
	v_pk_add_f32 v[156:157], v[140:141], v[112:113]
	s_nop 0
	v_mov_b32_dpp v114, v158 row_ror:1 row_mask:0xf bank_mask:0xf
	v_mul_f32_e32 v112, 0xbfb8aa3b, v156
	v_exp_f32_e32 v212, v112
	v_mov_b32_dpp v158, v159 row_ror:15 row_mask:0xf bank_mask:0xf
	v_cndmask_b32_e64 v159, v106, v98, s[6:7]
	s_nop 1
	v_mov_b32_dpp v208, v159 row_ror:15 row_mask:0xf bank_mask:0xf
	v_cndmask_b32_e64 v159, v111, v119, s[4:5]
	s_nop 1
	v_mov_b32_dpp v119, v159 row_ror:1 row_mask:0xf bank_mask:0xf
	v_cndmask_b32_e64 v159, v107, v115, s[4:5]
	v_pk_fma_f32 v[118:119], v[122:123], v[118:119], v[214:215]
; __device__ __forceinline__ void st_bf4(bf16_t* p, f32x4 v) { u32x2 w; w.x = pk2(v[0], v[1]); w.y = pk2(v[2], v[3]); *(u32x2*)p = w; }
; __device__ __forceinline__ float sigmoidf_(float x) { return __builtin_amdgcn_rcpf(1.f + __expf(-x)); }
; __device__ __forceinline__ float dpp_ror1(float v) { return __int_as_float(__builtin_amdgcn_update_dpp(0, __float_as_int(v), 0x121, 0xf, 0xf, false)); }
; __device__ __forceinline__ float dpp_rol1(float v) { return __int_as_float(__builtin_amdgcn_update_dpp(0, __float_as_int(v), 0x12F, 0xf, 0xf, false)); }
;     __device__ __forceinline__ void tile(const f32x4 (&acc)[2][2][4][2], const Unit& u, int wr, int wc, int fr, int fq) const {
;     ...
;                     for (int i = 0; i < 4; ++i) {
;                         const float xv = acc[ai][0][m][n][i], xg = acc[ai][1][m][n][i];
;                         const float uv = m > 0 ? acc[ai][0][m > 0 ? m - 1 : 0][n][i] : 0.f, ug = m > 0 ? acc[ai][1][m > 0 ? m - 1 : 0][n][i] : 0.f;
;                         const float dv = m < 3 ? acc[ai][0][m < 3 ? m + 1 : 3][n][i] : 0.f, dg = m < 3 ? acc[ai][1][m < 3 ? m + 1 : 3][n][i] : 0.f;
;                         const float pv = dpp_ror1(fr == 15 ? uv : xv), pg = dpp_ror1(fr == 15 ? ug : xg);
;                         const float nv = dpp_rol1(fr == 0 ? dv : xv), ng = dpp_rol1(fr == 0 ? dg : xg);
;                         const float yv = wv0[i] * pv + wv1[i] * xv + wv2[i] * nv + bv[i];
;                         const float yg = wg0[i] * pg + wg1[i] * xg + wg2[i] * ng + bg[i];
;                         r[i] = yg * sigmoidf_(yg) * yv;
;                     }
;                     st_bf4(ACT + (size_t)(u.pm * BM + ai * HALF + wr * 64 + m * 16 + fr) * FF + cv, r);
	s_nop 0
	v_mov_b32_dpp v115, v159 row_ror:1 row_mask:0xf bank_mask:0xf
	v_pk_fma_f32 v[114:115], v[134:135], v[114:115], v[210:211]
	s_nop 0
	v_mov_b32_dpp v159, v171 row_ror:15 row_mask:0xf bank_mask:0xf
	v_cndmask_b32_e64 v171, v107, v99, s[6:7]
	v_pk_fma_f32 v[118:119], v[126:127], v[158:159], v[118:119]
	s_nop 0
	v_mov_b32_dpp v209, v171 row_ror:15 row_mask:0xf bank_mask:0xf
	v_add_u32_e32 v171, s17, v198
	v_mad_i64_i32 v[112:113], s[28:29], v171, s46, v[184:185]
	v_add_f32_e32 v171, 1.0, v212
	v_mul_f32_e32 v212, 0xbfb8aa3b, v157
	v_exp_f32_e32 v213, v212
	v_rcp_f32_e32 v212, v171
	v_pk_fma_f32 v[114:115], v[138:139], v[208:209], v[114:115]
	v_pk_add_f32 v[118:119], v[130:131], v[118:119]
	v_add_f32_e32 v171, 1.0, v213
	v_rcp_f32_e32 v213, v171
	v_pk_add_f32 v[114:115], v[142:143], v[114:115]
	v_lshl_add_u64 v[112:113], v[112:113], 0, v[186:187]
	v_pk_mul_f32 v[154:155], v[156:157], v[212:213]
	s_nop 0
	v_pk_mul_f32 v[116:117], v[116:117], v[154:155]
	v_mul_f32_e32 v154, 0xbfb8aa3b, v114
	v_exp_f32_e32 v154, v154
	v_mul_f32_e32 v155, 0xbfb8aa3b, v115
	v_exp_f32_e32 v155, v155
	v_cvt_pk_bf16_f32 v116, v116, v117
	v_add_f32_e32 v117, 1.0, v154
	v_rcp_f32_e32 v154, v117
	v_add_f32_e32 v117, 1.0, v155
	v_rcp_f32_e32 v155, v117
	v_cndmask_b32_e64 v156, v99, 0, s[6:7]
	v_pk_mul_f32 v[114:115], v[114:115], v[154:155]
	s_nop 0
	v_pk_mul_f32 v[114:115], v[118:119], v[114:115]
	v_cndmask_b32_e64 v118, v97, 0, s[6:7]
	v_cvt_pk_bf16_f32 v117, v114, v115
	v_cndmask_b32_e64 v114, v100, v108, s[4:5]
	v_cndmask_b32_e64 v115, v100, 0, s[6:7]
	global_store_dwordx2 v[112:113], v[116:117], off
	v_mov_b32_dpp v108, v114 row_ror:1 row_mask:0xf bank_mask:0xf
	v_cndmask_b32_e64 v114, v96, v104, s[4:5]
	v_cndmask_b32_e64 v117, v101, 0, s[6:7]
	s_nop 0
	v_mov_b32_dpp v104, v114 row_ror:1 row_mask:0xf bank_mask:0xf
	v_cndmask_b32_e64 v119, v102, 0, s[6:7]
	v_mov_b32_dpp v114, v115 row_ror:15 row_mask:0xf bank_mask:0xf
	v_cndmask_b32_e64 v115, v96, 0, s[6:7]
	v_cndmask_b32_e64 v155, v103, 0, s[6:7]
	s_nop 0
	v_mov_b32_dpp v116, v115 row_ror:15 row_mask:0xf bank_mask:0xf
	v_cndmask_b32_e64 v115, v101, v109, s[4:5]
	v_pk_mul_f32 v[100:101], v[100:101], v[144:145]
	s_nop 0
	v_mov_b32_dpp v109, v115 row_ror:1 row_mask:0xf bank_mask:0xf
	v_cndmask_b32_e64 v115, v97, v105, s[4:5]
	v_pk_mul_f32 v[96:97], v[96:97], v[148:149]
	v_pk_fma_f32 v[100:101], v[120:121], v[108:109], v[100:101]
	v_mov_b32_dpp v105, v115 row_ror:1 row_mask:0xf bank_mask:0xf
	v_pk_fma_f32 v[96:97], v[132:133], v[104:105], v[96:97]
	v_mov_b32_dpp v115, v117 row_ror:15 row_mask:0xf bank_mask:0xf
	v_pk_fma_f32 v[100:101], v[124:125], v[114:115], v[100:101]
	v_mov_b32_dpp v117, v118 row_ror:15 row_mask:0xf bank_mask:0xf
	v_pk_fma_f32 v[96:97], v[136:137], v[116:117], v[96:97]
	v_cndmask_b32_e64 v118, v102, v110, s[4:5]
	v_pk_add_f32 v[104:105], v[140:141], v[96:97]
	s_nop 0
	v_mul_f32_e32 v96, 0xbfb8aa3b, v104
	v_mul_f32_e32 v117, 0xbfb8aa3b, v105
	v_mov_b32_dpp v110, v118 row_ror:1 row_mask:0xf bank_mask:0xf
	v_cndmask_b32_e64 v118, v98, v106, s[4:5]
	v_exp_f32_e32 v116, v96
	v_exp_f32_e32 v117, v117
	v_mov_b32_dpp v106, v118 row_ror:1 row_mask:0xf bank_mask:0xf
	v_add_f32_e32 v116, 1.0, v116
	v_add_f32_e32 v117, 1.0, v117
	v_mov_b32_dpp v118, v119 row_ror:15 row_mask:0xf bank_mask:0xf
	v_cndmask_b32_e64 v119, v98, 0, s[6:7]
	v_rcp_f32_e32 v116, v116
	v_rcp_f32_e32 v117, v117
	v_mov_b32_dpp v154, v119 row_ror:15 row_mask:0xf bank_mask:0xf
	v_cndmask_b32_e64 v119, v103, v111, s[4:5]
	v_pk_add_f32 v[100:101], v[128:129], v[100:101]
	v_pk_mul_f32 v[104:105], v[104:105], v[116:117]
	v_mov_b32_dpp v111, v119 row_ror:1 row_mask:0xf bank_mask:0xf
	v_cndmask_b32_e64 v119, v99, v107, s[4:5]
	v_pk_mul_f32 v[98:99], v[98:99], v[150:151]
	v_pk_mul_f32 v[100:101], v[100:101], v[104:105]
	v_mov_b32_dpp v107, v119 row_ror:1 row_mask:0xf bank_mask:0xf
	v_pk_fma_f32 v[98:99], v[134:135], v[106:107], v[98:99]
	v_cvt_pk_bf16_f32 v100, v100, v101
	v_mov_b32_dpp v119, v155 row_ror:15 row_mask:0xf bank_mask:0xf
	v_pk_mul_f32 v[102:103], v[102:103], v[146:147]
	v_cndmask_b32_e64 v106, v89, v81, s[6:7]
	v_mov_b32_dpp v155, v156 row_ror:15 row_mask:0xf bank_mask:0xf
	v_pk_fma_f32 v[98:99], v[138:139], v[154:155], v[98:99]
	v_pk_fma_f32 v[102:103], v[122:123], v[110:111], v[102:103]
	v_pk_add_f32 v[98:99], v[142:143], v[98:99]
	v_pk_fma_f32 v[102:103], v[126:127], v[118:119], v[102:103]
	v_mul_f32_e32 v104, 0xbfb8aa3b, v98
	v_exp_f32_e32 v104, v104
	v_mul_f32_e32 v105, 0xbfb8aa3b, v99
	v_exp_f32_e32 v105, v105
	v_add_u32_e32 v156, s17, v199
	v_add_f32_e32 v101, 1.0, v104
	v_rcp_f32_e32 v104, v101
	v_add_f32_e32 v101, 1.0, v105
	v_rcp_f32_e32 v105, v101
	v_pk_add_f32 v[102:103], v[130:131], v[102:103]
	v_mad_i64_i32 v[96:97], s[28:29], v156, s46, v[184:185]
	v_pk_mul_f32 v[98:99], v[98:99], v[104:105]
	v_lshl_add_u64 v[96:97], v[96:97], 0, v[186:187]
	v_pk_mul_f32 v[98:99], v[102:103], v[98:99]
	s_nop 0
	v_cvt_pk_bf16_f32 v101, v98, v99
	global_store_dwordx2 v[96:97], v[100:101], off
	v_cndmask_b32_e64 v98, v92, 0, s[4:5]
	v_cndmask_b32_e64 v99, v88, 0, s[4:5]
	s_nop 0
	v_mov_b32_dpp v100, v98 row_ror:1 row_mask:0xf bank_mask:0xf
	v_cndmask_b32_e64 v103, v89, 0, s[4:5]
	v_mov_b32_dpp v98, v99 row_ror:1 row_mask:0xf bank_mask:0xf
	v_cndmask_b32_e64 v99, v92, v84, s[6:7]
	v_cndmask_b32_e64 v105, v93, v85, s[6:7]
	v_cndmask_b32_e64 v107, v94, 0, s[4:5]
	v_mov_b32_dpp v102, v99 row_ror:15 row_mask:0xf bank_mask:0xf
	v_cndmask_b32_e64 v99, v88, v80, s[6:7]
	v_cndmask_b32_e64 v109, v95, 0, s[4:5]
	s_nop 0
	v_mov_b32_dpp v104, v99 row_ror:15 row_mask:0xf bank_mask:0xf
	v_cndmask_b32_e64 v99, v93, 0, s[4:5]
	v_cndmask_b32_e64 v111, v91, 0, s[4:5]
; __device__ __forceinline__ void st_bf4(bf16_t* p, f32x4 v) { u32x2 w; w.x = pk2(v[0], v[1]); w.y = pk2(v[2], v[3]); *(u32x2*)p = w; }
; __device__ __forceinline__ float sigmoidf_(float x) { return __builtin_amdgcn_rcpf(1.f + __expf(-x)); }
; __device__ __forceinline__ float dpp_ror1(float v) { return __int_as_float(__builtin_amdgcn_update_dpp(0, __float_as_int(v), 0x121, 0xf, 0xf, false)); }
; __device__ __forceinline__ float dpp_rol1(float v) { return __int_as_float(__builtin_amdgcn_update_dpp(0, __float_as_int(v), 0x12F, 0xf, 0xf, false)); }
;     __device__ __forceinline__ void tile(const f32x4 (&acc)[2][2][4][2], const Unit& u, int wr, int wc, int fr, int fq) const {
;     ...
;                     for (int i = 0; i < 4; ++i) {
;                         const float xv = acc[ai][0][m][n][i], xg = acc[ai][1][m][n][i];
;                         const float uv = m > 0 ? acc[ai][0][m > 0 ? m - 1 : 0][n][i] : 0.f, ug = m > 0 ? acc[ai][1][m > 0 ? m - 1 : 0][n][i] : 0.f;
;                         const float dv = m < 3 ? acc[ai][0][m < 3 ? m + 1 : 3][n][i] : 0.f, dg = m < 3 ? acc[ai][1][m < 3 ? m + 1 : 3][n][i] : 0.f;
;                         const float pv = dpp_ror1(fr == 15 ? uv : xv), pg = dpp_ror1(fr == 15 ? ug : xg);
;                         const float nv = dpp_rol1(fr == 0 ? dv : xv), ng = dpp_rol1(fr == 0 ? dg : xg);
;                         const float yv = wv0[i] * pv + wv1[i] * xv + wv2[i] * nv + bv[i];
;                         const float yg = wg0[i] * pg + wg1[i] * xg + wg2[i] * ng + bg[i];
;                         r[i] = yg * sigmoidf_(yg) * yv;
;                     }
;                     st_bf4(ACT + (size_t)(u.pm * BM + ai * HALF + wr * 64 + m * 16 + fr) * FF + cv, r);
	v_cndmask_b32_e64 v115, v95, v87, s[6:7]
	v_mov_b32_dpp v101, v99 row_ror:1 row_mask:0xf bank_mask:0xf
	v_cndmask_b32_e64 v116, v91, v83, s[6:7]
	v_add_u32_e32 v118, s17, v200
	v_mov_b32_dpp v99, v103 row_ror:1 row_mask:0xf bank_mask:0xf
	v_pk_mul_f32 v[156:157], v[92:93], v[144:145]
	v_pk_mul_f32 v[154:155], v[94:95], v[146:147]
	v_mov_b32_dpp v103, v105 row_ror:15 row_mask:0xf bank_mask:0xf
	v_pk_fma_f32 v[100:101], v[120:121], v[100:101], v[156:157]
	s_nop 0
	v_mov_b32_dpp v105, v106 row_ror:15 row_mask:0xf bank_mask:0xf
	v_pk_fma_f32 v[100:101], v[124:125], v[102:103], v[100:101]
	s_nop 0
	v_mov_b32_dpp v106, v107 row_ror:1 row_mask:0xf bank_mask:0xf
	v_cndmask_b32_e64 v107, v90, 0, s[4:5]
	v_pk_add_f32 v[100:101], v[128:129], v[100:101]
	s_nop 0
	v_mov_b32_dpp v108, v107 row_ror:1 row_mask:0xf bank_mask:0xf
	v_cndmask_b32_e64 v107, v94, v86, s[6:7]
	s_nop 1
	v_mov_b32_dpp v110, v107 row_ror:15 row_mask:0xf bank_mask:0xf
	v_cndmask_b32_e64 v107, v90, v82, s[6:7]
	s_nop 1
	v_mov_b32_dpp v114, v107 row_ror:15 row_mask:0xf bank_mask:0xf
	s_nop 1
	v_mov_b32_dpp v107, v109 row_ror:1 row_mask:0xf bank_mask:0xf
	v_pk_fma_f32 v[106:107], v[122:123], v[106:107], v[154:155]
	s_nop 0
	v_mov_b32_dpp v109, v111 row_ror:1 row_mask:0xf bank_mask:0xf
	s_nop 1
	v_mov_b32_dpp v111, v115 row_ror:15 row_mask:0xf bank_mask:0xf
	v_pk_fma_f32 v[106:107], v[126:127], v[110:111], v[106:107]
	v_add_u32_e32 v110, s17, v201
	v_mov_b32_dpp v115, v116 row_ror:15 row_mask:0xf bank_mask:0xf
	v_pk_mul_f32 v[116:117], v[88:89], v[148:149]
	v_pk_add_f32 v[106:107], v[130:131], v[106:107]
	v_pk_fma_f32 v[98:99], v[132:133], v[98:99], v[116:117]
	v_pk_mul_f32 v[116:117], v[90:91], v[150:151]
	v_pk_fma_f32 v[98:99], v[136:137], v[104:105], v[98:99]
	s_nop 0
	v_pk_add_f32 v[104:105], v[140:141], v[98:99]
	s_nop 0
	v_mul_f32_e32 v98, 0xbfb8aa3b, v104
	v_exp_f32_e32 v119, v98
	v_mad_i64_i32 v[98:99], s[28:29], v118, s46, v[184:185]
	v_lshl_add_u64 v[98:99], v[98:99], 0, v[186:187]
	v_add_f32_e32 v118, 1.0, v119
	v_mul_f32_e32 v119, 0xbfb8aa3b, v105
	v_exp_f32_e32 v119, v119
	v_rcp_f32_e32 v118, v118
	v_add_f32_e32 v119, 1.0, v119
	v_rcp_f32_e32 v119, v119
	s_nop 0
	v_pk_mul_f32 v[102:103], v[104:105], v[118:119]
	s_nop 0
	v_pk_mul_f32 v[100:101], v[100:101], v[102:103]
	v_pk_fma_f32 v[102:103], v[134:135], v[108:109], v[116:117]
	v_cvt_pk_bf16_f32 v100, v100, v101
	v_pk_fma_f32 v[102:103], v[138:139], v[114:115], v[102:103]
	v_cndmask_b32_e64 v108, v83, v75, s[6:7]
	v_pk_add_f32 v[102:103], v[142:143], v[102:103]
	v_pk_mul_f32 v[116:117], v[84:85], v[144:145]
	v_mul_f32_e32 v104, 0xbfb8aa3b, v102
	v_exp_f32_e32 v104, v104
	v_mul_f32_e32 v105, 0xbfb8aa3b, v103
	v_exp_f32_e32 v105, v105
	v_pk_mul_f32 v[114:115], v[86:87], v[146:147]
	v_add_f32_e32 v101, 1.0, v104
	v_rcp_f32_e32 v104, v101
	v_add_f32_e32 v101, 1.0, v105
	v_rcp_f32_e32 v105, v101
	v_cndmask_b32_e64 v119, v63, 0, s[4:5]
	v_pk_mul_f32 v[102:103], v[102:103], v[104:105]
	s_nop 0
	v_pk_mul_f32 v[102:103], v[106:107], v[102:103]
	v_cndmask_b32_e64 v104, v81, v73, s[6:7]
	v_cvt_pk_bf16_f32 v101, v102, v103
	global_store_dwordx2 v[98:99], v[100:101], off
	v_cndmask_b32_e64 v100, v84, v92, s[4:5]
	v_cndmask_b32_e64 v101, v80, v72, s[6:7]
	s_nop 0
	v_mov_b32_dpp v92, v100 row_ror:1 row_mask:0xf bank_mask:0xf
	v_cndmask_b32_e64 v100, v80, v88, s[4:5]
	v_cndmask_b32_e64 v105, v86, v78, s[6:7]
	s_nop 0
	v_mov_b32_dpp v88, v100 row_ror:1 row_mask:0xf bank_mask:0xf
	v_cndmask_b32_e64 v100, v84, v76, s[6:7]
	v_cndmask_b32_e64 v107, v87, v79, s[6:7]
	s_nop 0
	v_mov_b32_dpp v102, v100 row_ror:15 row_mask:0xf bank_mask:0xf
	s_nop 1
	v_mov_b32_dpp v100, v101 row_ror:15 row_mask:0xf bank_mask:0xf
	v_cndmask_b32_e64 v101, v85, v93, s[4:5]
	s_nop 1
	v_mov_b32_dpp v93, v101 row_ror:1 row_mask:0xf bank_mask:0xf
	v_cndmask_b32_e64 v101, v81, v89, s[4:5]
	v_pk_fma_f32 v[92:93], v[120:121], v[92:93], v[116:117]
	v_cndmask_b32_e64 v116, v57, v49, s[6:7]
	v_mov_b32_dpp v89, v101 row_ror:1 row_mask:0xf bank_mask:0xf
	v_cndmask_b32_e64 v101, v85, v77, s[6:7]
	v_cndmask_b32_e64 v117, v62, 0, s[4:5]
	s_nop 0
	v_mov_b32_dpp v103, v101 row_ror:15 row_mask:0xf bank_mask:0xf
	v_pk_fma_f32 v[92:93], v[124:125], v[102:103], v[92:93]
	v_cndmask_b32_e64 v102, v75, v67, s[6:7]
	v_mov_b32_dpp v101, v104 row_ror:15 row_mask:0xf bank_mask:0xf
	v_cndmask_b32_e64 v104, v86, v94, s[4:5]
	v_pk_add_f32 v[92:93], v[128:129], v[92:93]
	s_nop 0
	v_mov_b32_dpp v94, v104 row_ror:1 row_mask:0xf bank_mask:0xf
	v_cndmask_b32_e64 v104, v82, v90, s[4:5]
	s_nop 1
	v_mov_b32_dpp v90, v104 row_ror:1 row_mask:0xf bank_mask:0xf
	s_nop 1
	v_mov_b32_dpp v104, v105 row_ror:15 row_mask:0xf bank_mask:0xf
	v_cndmask_b32_e64 v105, v82, v74, s[6:7]
	s_nop 1
	v_mov_b32_dpp v106, v105 row_ror:15 row_mask:0xf bank_mask:0xf
	v_cndmask_b32_e64 v105, v87, v95, s[4:5]
	s_nop 1
	v_mov_b32_dpp v95, v105 row_ror:1 row_mask:0xf bank_mask:0xf
	v_cndmask_b32_e64 v105, v83, v91, s[4:5]
	v_pk_fma_f32 v[94:95], v[122:123], v[94:95], v[114:115]
	s_nop 0
	v_mov_b32_dpp v91, v105 row_ror:1 row_mask:0xf bank_mask:0xf
	v_cndmask_b32_e64 v115, v61, v53, s[6:7]
	s_nop 0
	v_mov_b32_dpp v105, v107 row_ror:15 row_mask:0xf bank_mask:0xf
	v_pk_fma_f32 v[94:95], v[126:127], v[104:105], v[94:95]
	v_add_u32_e32 v104, s17, v202
	v_mov_b32_dpp v107, v108 row_ror:15 row_mask:0xf bank_mask:0xf
	v_pk_mul_f32 v[108:109], v[80:81], v[148:149]
	v_pk_add_f32 v[94:95], v[130:131], v[94:95]
	v_pk_fma_f32 v[88:89], v[132:133], v[88:89], v[108:109]
	v_pk_mul_f32 v[108:109], v[82:83], v[150:151]
	v_pk_fma_f32 v[88:89], v[136:137], v[100:101], v[88:89]
	v_pk_fma_f32 v[90:91], v[134:135], v[90:91], v[108:109]
; __device__ __forceinline__ void st_bf4(bf16_t* p, f32x4 v) { u32x2 w; w.x = pk2(v[0], v[1]); w.y = pk2(v[2], v[3]); *(u32x2*)p = w; }
; __device__ __forceinline__ float sigmoidf_(float x) { return __builtin_amdgcn_rcpf(1.f + __expf(-x)); }
; __device__ __forceinline__ float dpp_ror1(float v) { return __int_as_float(__builtin_amdgcn_update_dpp(0, __float_as_int(v), 0x121, 0xf, 0xf, false)); }
; __device__ __forceinline__ float dpp_rol1(float v) { return __int_as_float(__builtin_amdgcn_update_dpp(0, __float_as_int(v), 0x12F, 0xf, 0xf, false)); }
;     __device__ __forceinline__ void tile(const f32x4 (&acc)[2][2][4][2], const Unit& u, int wr, int wc, int fr, int fq) const {
;     ...
;                     for (int i = 0; i < 4; ++i) {
;                         const float xv = acc[ai][0][m][n][i], xg = acc[ai][1][m][n][i];
;                         const float uv = m > 0 ? acc[ai][0][m > 0 ? m - 1 : 0][n][i] : 0.f, ug = m > 0 ? acc[ai][1][m > 0 ? m - 1 : 0][n][i] : 0.f;
;                         const float dv = m < 3 ? acc[ai][0][m < 3 ? m + 1 : 3][n][i] : 0.f, dg = m < 3 ? acc[ai][1][m < 3 ? m + 1 : 3][n][i] : 0.f;
;                         const float pv = dpp_ror1(fr == 15 ? uv : xv), pg = dpp_ror1(fr == 15 ? ug : xg);
;                         const float nv = dpp_rol1(fr == 0 ? dv : xv), ng = dpp_rol1(fr == 0 ? dg : xg);
;                         const float yv = wv0[i] * pv + wv1[i] * xv + wv2[i] * nv + bv[i];
;                         const float yg = wg0[i] * pg + wg1[i] * xg + wg2[i] * ng + bg[i];
;                         r[i] = yg * sigmoidf_(yg) * yv;
;                     }
;                     st_bf4(ACT + (size_t)(u.pm * BM + ai * HALF + wr * 64 + m * 16 + fr) * FF + cv, r);
	v_pk_add_f32 v[88:89], v[140:141], v[88:89]
	v_pk_fma_f32 v[90:91], v[138:139], v[106:107], v[90:91]
	v_mul_f32_e32 v100, 0xbfb8aa3b, v88
	v_exp_f32_e32 v111, v100
	v_mad_i64_i32 v[100:101], s[28:29], v110, s46, v[184:185]
	v_pk_add_f32 v[90:91], v[142:143], v[90:91]
	v_add_f32_e32 v110, 1.0, v111
	v_mul_f32_e32 v111, 0xbfb8aa3b, v89
	v_exp_f32_e32 v111, v111
	v_rcp_f32_e32 v110, v110
	v_lshl_add_u64 v[100:101], v[100:101], 0, v[186:187]
	v_pk_mul_f32 v[108:109], v[76:77], v[144:145]
	v_add_f32_e32 v111, 1.0, v111
	v_rcp_f32_e32 v111, v111
	v_pk_mul_f32 v[106:107], v[78:79], v[146:147]
	v_pk_mul_f32 v[88:89], v[88:89], v[110:111]
	s_nop 0
	v_pk_mul_f32 v[88:89], v[92:93], v[88:89]
	v_mul_f32_e32 v92, 0xbfb8aa3b, v90
	v_exp_f32_e32 v92, v92
	v_mul_f32_e32 v93, 0xbfb8aa3b, v91
	v_exp_f32_e32 v93, v93
	v_cvt_pk_bf16_f32 v88, v88, v89
	v_add_f32_e32 v89, 1.0, v92
	v_rcp_f32_e32 v92, v89
	v_add_f32_e32 v89, 1.0, v93
	v_rcp_f32_e32 v93, v89
	v_cndmask_b32_e64 v111, v57, 0, s[4:5]
	v_pk_mul_f32 v[90:91], v[90:91], v[92:93]
	s_nop 0
	v_pk_mul_f32 v[90:91], v[94:95], v[90:91]
	v_cndmask_b32_e64 v92, v73, v65, s[6:7]
	v_cvt_pk_bf16_f32 v89, v90, v91
	global_store_dwordx2 v[100:101], v[88:89], off
	v_cndmask_b32_e64 v88, v76, v84, s[4:5]
	v_cndmask_b32_e64 v89, v76, v68, s[6:7]
	s_nop 0
	v_mov_b32_dpp v84, v88 row_ror:1 row_mask:0xf bank_mask:0xf
	v_cndmask_b32_e64 v88, v72, v80, s[4:5]
	v_cndmask_b32_e64 v91, v77, v69, s[6:7]
	v_cndmask_b32_e64 v93, v78, v70, s[6:7]
	v_mov_b32_dpp v80, v88 row_ror:1 row_mask:0xf bank_mask:0xf
	v_cndmask_b32_e64 v95, v79, v71, s[6:7]
	v_mov_b32_dpp v88, v89 row_ror:15 row_mask:0xf bank_mask:0xf
	v_cndmask_b32_e64 v89, v72, v64, s[6:7]
	s_nop 1
	v_mov_b32_dpp v90, v89 row_ror:15 row_mask:0xf bank_mask:0xf
	v_cndmask_b32_e64 v89, v77, v85, s[4:5]
	s_nop 1
	v_mov_b32_dpp v85, v89 row_ror:1 row_mask:0xf bank_mask:0xf
	v_cndmask_b32_e64 v89, v73, v81, s[4:5]
	v_pk_fma_f32 v[84:85], v[120:121], v[84:85], v[108:109]
	s_nop 0
	v_mov_b32_dpp v81, v89 row_ror:1 row_mask:0xf bank_mask:0xf
	v_cndmask_b32_e64 v109, v61, 0, s[4:5]
	s_nop 0
	v_mov_b32_dpp v89, v91 row_ror:15 row_mask:0xf bank_mask:0xf
	v_pk_fma_f32 v[84:85], v[124:125], v[88:89], v[84:85]
	v_cndmask_b32_e64 v88, v67, 0, s[6:7]
	v_mov_b32_dpp v91, v92 row_ror:15 row_mask:0xf bank_mask:0xf
	v_cndmask_b32_e64 v92, v78, v86, s[4:5]
	v_pk_add_f32 v[84:85], v[128:129], v[84:85]
	s_nop 0
	v_mov_b32_dpp v86, v92 row_ror:1 row_mask:0xf bank_mask:0xf
	v_cndmask_b32_e64 v92, v74, v82, s[4:5]
	s_nop 1
	v_mov_b32_dpp v82, v92 row_ror:1 row_mask:0xf bank_mask:0xf
	s_nop 1
	v_mov_b32_dpp v92, v93 row_ror:15 row_mask:0xf bank_mask:0xf
	v_cndmask_b32_e64 v93, v74, v66, s[6:7]
	s_nop 1
	v_mov_b32_dpp v94, v93 row_ror:15 row_mask:0xf bank_mask:0xf
	v_cndmask_b32_e64 v93, v79, v87, s[4:5]
	s_nop 1
	v_mov_b32_dpp v87, v93 row_ror:1 row_mask:0xf bank_mask:0xf
	v_cndmask_b32_e64 v93, v75, v83, s[4:5]
	v_pk_fma_f32 v[86:87], v[122:123], v[86:87], v[106:107]
	v_cndmask_b32_e64 v107, v60, 0, s[4:5]
	v_mov_b32_dpp v83, v93 row_ror:1 row_mask:0xf bank_mask:0xf
	s_nop 0
	v_mov_b32_dpp v93, v95 row_ror:15 row_mask:0xf bank_mask:0xf
	v_pk_fma_f32 v[86:87], v[126:127], v[92:93], v[86:87]
	v_mov_b32_dpp v106, v107 row_ror:1 row_mask:0xf bank_mask:0xf
	v_mov_b32_dpp v95, v102 row_ror:15 row_mask:0xf bank_mask:0xf
	v_pk_mul_f32 v[102:103], v[72:73], v[148:149]
	v_pk_add_f32 v[86:87], v[130:131], v[86:87]
	v_pk_fma_f32 v[80:81], v[132:133], v[80:81], v[102:103]
	v_cndmask_b32_e64 v107, v56, 0, s[4:5]
	v_pk_fma_f32 v[80:81], v[136:137], v[90:91], v[80:81]
	s_nop 0
	v_pk_add_f32 v[80:81], v[140:141], v[80:81]
	v_mov_b32_dpp v108, v107 row_ror:1 row_mask:0xf bank_mask:0xf
	v_mul_f32_e32 v90, 0xbfb8aa3b, v80
	v_exp_f32_e32 v105, v90
	v_mad_i64_i32 v[90:91], s[28:29], v104, s46, v[184:185]
	v_lshl_add_u64 v[102:103], v[90:91], 0, v[186:187]
	v_add_f32_e32 v104, 1.0, v105
	v_mul_f32_e32 v105, 0xbfb8aa3b, v81
	v_exp_f32_e32 v105, v105
	v_rcp_f32_e32 v104, v104
	v_pk_mul_f32 v[90:91], v[74:75], v[150:151]
	v_cndmask_b32_e64 v107, v60, v52, s[6:7]
	v_add_f32_e32 v105, 1.0, v105
	v_rcp_f32_e32 v105, v105
	v_pk_fma_f32 v[82:83], v[134:135], v[82:83], v[90:91]
	v_mov_b32_dpp v110, v107 row_ror:15 row_mask:0xf bank_mask:0xf
	v_pk_fma_f32 v[82:83], v[138:139], v[94:95], v[82:83]
	v_pk_mul_f32 v[80:81], v[80:81], v[104:105]
	v_pk_add_f32 v[82:83], v[142:143], v[82:83]
	v_pk_mul_f32 v[80:81], v[84:85], v[80:81]
	v_mul_f32_e32 v84, 0xbfb8aa3b, v82
	v_exp_f32_e32 v84, v84
	v_mul_f32_e32 v85, 0xbfb8aa3b, v83
	v_exp_f32_e32 v85, v85
	v_cvt_pk_bf16_f32 v80, v80, v81
	v_add_f32_e32 v81, 1.0, v84
	v_rcp_f32_e32 v84, v81
	v_add_f32_e32 v81, 1.0, v85
	v_rcp_f32_e32 v85, v81
	v_cndmask_b32_e64 v107, v56, v48, s[6:7]
	v_pk_mul_f32 v[82:83], v[82:83], v[84:85]
	s_nop 0
	v_pk_mul_f32 v[82:83], v[86:87], v[82:83]
	v_cndmask_b32_e64 v84, v65, 0, s[6:7]
	v_cvt_pk_bf16_f32 v81, v82, v83
	global_store_dwordx2 v[102:103], v[80:81], off
	v_cndmask_b32_e64 v80, v68, v76, s[4:5]
	v_cndmask_b32_e64 v81, v68, 0, s[6:7]
	s_nop 0
	v_mov_b32_dpp v76, v80 row_ror:1 row_mask:0xf bank_mask:0xf
	v_cndmask_b32_e64 v80, v64, v72, s[4:5]
	v_cndmask_b32_e64 v83, v69, 0, s[6:7]
	v_cndmask_b32_e64 v85, v70, 0, s[6:7]
	v_mov_b32_dpp v72, v80 row_ror:1 row_mask:0xf bank_mask:0xf
	v_cndmask_b32_e64 v87, v71, 0, s[6:7]
	v_mov_b32_dpp v80, v81 row_ror:15 row_mask:0xf bank_mask:0xf
	v_cndmask_b32_e64 v81, v64, 0, s[6:7]
	v_mov_b32_dpp v114, v107 row_ror:15 row_mask:0xf bank_mask:0xf
	s_nop 0
	v_mov_b32_dpp v82, v81 row_ror:15 row_mask:0xf bank_mask:0xf
	v_cndmask_b32_e64 v81, v69, v77, s[4:5]
	v_pk_mul_f32 v[68:69], v[68:69], v[144:145]
; __device__ __forceinline__ void st_bf4(bf16_t* p, f32x4 v) { u32x2 w; w.x = pk2(v[0], v[1]); w.y = pk2(v[2], v[3]); *(u32x2*)p = w; }
; __device__ __forceinline__ float sigmoidf_(float x) { return __builtin_amdgcn_rcpf(1.f + __expf(-x)); }
; __device__ __forceinline__ float dpp_ror1(float v) { return __int_as_float(__builtin_amdgcn_update_dpp(0, __float_as_int(v), 0x121, 0xf, 0xf, false)); }
; __device__ __forceinline__ float dpp_rol1(float v) { return __int_as_float(__builtin_amdgcn_update_dpp(0, __float_as_int(v), 0x12F, 0xf, 0xf, false)); }
;     __device__ __forceinline__ void tile(const f32x4 (&acc)[2][2][4][2], const Unit& u, int wr, int wc, int fr, int fq) const {
;     ...
;         for (int n = 0; n < 2; ++n) {
;             const int cv = 128 * u.pn + 32 * wc + 16 * n + 4 * fq, cg = FF + cv;
;             const f32x4 wv0 = *(const f32x4*)(cw + cv), wv1 = *(const f32x4*)(cw + F2 + cv), wv2 = *(const f32x4*)(cw + 2 * F2 + cv), bv = *(const f32x4*)(cb + cv);
;             const f32x4 wg0 = *(const f32x4*)(cw + cg), wg1 = *(const f32x4*)(cw + F2 + cg), wg2 = *(const f32x4*)(cw + 2 * F2 + cg), bg = *(const f32x4*)(cb + cg);
; #pragma unroll
;             for (int ai = 0; ai < 2; ++ai)
; #pragma unroll
;                 for (int m = 0; m < 4; ++m) {
;                     f32x4 r;
; #pragma unroll
;                     for (int i = 0; i < 4; ++i) {
;                         const float xv = acc[ai][0][m][n][i], xg = acc[ai][1][m][n][i];
;                         const float uv = m > 0 ? acc[ai][0][m > 0 ? m - 1 : 0][n][i] : 0.f, ug = m > 0 ? acc[ai][1][m > 0 ? m - 1 : 0][n][i] : 0.f;
;                         const float dv = m < 3 ? acc[ai][0][m < 3 ? m + 1 : 3][n][i] : 0.f, dg = m < 3 ? acc[ai][1][m < 3 ? m + 1 : 3][n][i] : 0.f;
;                         const float pv = dpp_ror1(fr == 15 ? uv : xv), pg = dpp_ror1(fr == 15 ? ug : xg);
;                         const float nv = dpp_rol1(fr == 0 ? dv : xv), ng = dpp_rol1(fr == 0 ? dg : xg);
;                         const float yv = wv0[i] * pv + wv1[i] * xv + wv2[i] * nv + bv[i];
;                         const float yg = wg0[i] * pg + wg1[i] * xg + wg2[i] * ng + bg[i];
;                         r[i] = yg * sigmoidf_(yg) * yv;
;                     }
;                     st_bf4(ACT + (size_t)(u.pm * BM + ai * HALF + wr * 64 + m * 16 + fr) * FF + cv, r);
	v_mov_b32_dpp v107, v109 row_ror:1 row_mask:0xf bank_mask:0xf
	v_mov_b32_dpp v77, v81 row_ror:1 row_mask:0xf bank_mask:0xf
	v_cndmask_b32_e64 v81, v65, v73, s[4:5]
	v_pk_mul_f32 v[64:65], v[64:65], v[148:149]
	v_pk_fma_f32 v[68:69], v[120:121], v[76:77], v[68:69]
	v_mov_b32_dpp v73, v81 row_ror:1 row_mask:0xf bank_mask:0xf
	v_pk_fma_f32 v[64:65], v[132:133], v[72:73], v[64:65]
	v_mov_b32_dpp v81, v83 row_ror:15 row_mask:0xf bank_mask:0xf
	v_pk_fma_f32 v[68:69], v[124:125], v[80:81], v[68:69]
	v_mov_b32_dpp v109, v111 row_ror:1 row_mask:0xf bank_mask:0xf
	v_mov_b32_dpp v83, v84 row_ror:15 row_mask:0xf bank_mask:0xf
	v_cndmask_b32_e64 v84, v70, v78, s[4:5]
	v_pk_fma_f32 v[64:65], v[136:137], v[82:83], v[64:65]
	v_pk_add_f32 v[68:69], v[128:129], v[68:69]
	v_mov_b32_dpp v78, v84 row_ror:1 row_mask:0xf bank_mask:0xf
	v_cndmask_b32_e64 v84, v66, v74, s[4:5]
	v_pk_add_f32 v[64:65], v[140:141], v[64:65]
	s_nop 0
	v_mov_b32_dpp v74, v84 row_ror:1 row_mask:0xf bank_mask:0xf
	v_mul_f32_e32 v72, 0xbfb8aa3b, v64
	v_exp_f32_e32 v82, v72
	v_mov_b32_dpp v84, v85 row_ror:15 row_mask:0xf bank_mask:0xf
	v_cndmask_b32_e64 v85, v66, 0, s[6:7]
	v_mov_b32_dpp v111, v115 row_ror:15 row_mask:0xf bank_mask:0xf
	s_nop 0
	v_mov_b32_dpp v86, v85 row_ror:15 row_mask:0xf bank_mask:0xf
	v_cndmask_b32_e64 v85, v71, v79, s[4:5]
	v_pk_mul_f32 v[70:71], v[70:71], v[146:147]
	v_mov_b32_dpp v115, v116 row_ror:15 row_mask:0xf bank_mask:0xf
	v_mov_b32_dpp v79, v85 row_ror:1 row_mask:0xf bank_mask:0xf
	v_cndmask_b32_e64 v85, v67, v75, s[4:5]
	v_pk_mul_f32 v[66:67], v[66:67], v[150:151]
	v_pk_fma_f32 v[70:71], v[122:123], v[78:79], v[70:71]
	v_mov_b32_dpp v75, v85 row_ror:1 row_mask:0xf bank_mask:0xf
	v_pk_fma_f32 v[66:67], v[134:135], v[74:75], v[66:67]
	v_mov_b32_dpp v85, v87 row_ror:15 row_mask:0xf bank_mask:0xf
	v_pk_fma_f32 v[70:71], v[126:127], v[84:85], v[70:71]
	v_mov_b32_dpp v116, v117 row_ror:1 row_mask:0xf bank_mask:0xf
	v_mov_b32_dpp v87, v88 row_ror:15 row_mask:0xf bank_mask:0xf
	v_add_u32_e32 v88, s17, v203
	v_mad_i64_i32 v[72:73], s[28:29], v88, s46, v[184:185]
	v_lshl_add_u64 v[104:105], v[72:73], 0, v[186:187]
	v_mul_f32_e32 v73, 0xbfb8aa3b, v65
	v_exp_f32_e32 v73, v73
	v_add_f32_e32 v72, 1.0, v82
	v_rcp_f32_e32 v72, v72
	v_pk_fma_f32 v[66:67], v[138:139], v[86:87], v[66:67]
	v_add_f32_e32 v73, 1.0, v73
	v_rcp_f32_e32 v73, v73
	v_pk_add_f32 v[66:67], v[142:143], v[66:67]
	v_pk_add_f32 v[70:71], v[130:131], v[70:71]
	v_cndmask_b32_e64 v117, v58, 0, s[4:5]
	v_pk_mul_f32 v[64:65], v[64:65], v[72:73]
	s_nop 0
	v_pk_mul_f32 v[64:65], v[68:69], v[64:65]
	v_mul_f32_e32 v68, 0xbfb8aa3b, v66
	v_exp_f32_e32 v68, v68
	v_mul_f32_e32 v69, 0xbfb8aa3b, v67
	v_exp_f32_e32 v69, v69
	v_cvt_pk_bf16_f32 v64, v64, v65
	v_add_f32_e32 v65, 1.0, v68
	v_rcp_f32_e32 v68, v65
	v_add_f32_e32 v65, 1.0, v69
	v_rcp_f32_e32 v69, v65
	v_mov_b32_dpp v118, v117 row_ror:1 row_mask:0xf bank_mask:0xf
	v_cndmask_b32_e64 v117, v62, v54, s[6:7]
	v_pk_mul_f32 v[66:67], v[66:67], v[68:69]
	s_nop 0
	v_mov_b32_dpp v120, v117 row_ror:15 row_mask:0xf bank_mask:0xf
	v_pk_mul_f32 v[66:67], v[70:71], v[66:67]
	v_cndmask_b32_e64 v117, v58, v50, s[6:7]
	v_cvt_pk_bf16_f32 v65, v66, v67
	global_store_dwordx2 v[104:105], v[64:65], off
	v_mov_b32_dpp v122, v117 row_ror:15 row_mask:0xf bank_mask:0xf
	v_cndmask_b32_e64 v121, v59, 0, s[4:5]
	v_cndmask_b32_e64 v123, v63, v55, s[6:7]
	v_mov_b32_dpp v117, v119 row_ror:1 row_mask:0xf bank_mask:0xf
	v_cndmask_b32_e64 v126, v59, v51, s[6:7]
	v_pk_mul_f32 v[124:125], v[56:57], v[234:235]
	s_nop 0
	v_pk_fma_f32 v[108:109], v[230:231], v[108:109], v[124:125]
	v_mov_b32_dpp v119, v121 row_ror:1 row_mask:0xf bank_mask:0xf
	v_pk_fma_f32 v[108:109], v[238:239], v[114:115], v[108:109]
	s_nop 0
	v_pk_add_f32 v[108:109], v[242:243], v[108:109]
	v_pk_mul_f32 v[128:129], v[60:61], v[246:247]
	v_mul_f32_e32 v114, 0xbfb8aa3b, v108
	v_mul_f32_e32 v125, 0xbfb8aa3b, v109
	v_exp_f32_e32 v124, v114
	v_exp_f32_e32 v125, v125
	v_pk_fma_f32 v[106:107], v[250:251], v[106:107], v[128:129]
	v_mov_b32_dpp v121, v123 row_ror:15 row_mask:0xf bank_mask:0xf
	v_add_f32_e32 v124, 1.0, v124
	v_add_f32_e32 v125, 1.0, v125
	v_rcp_f32_e32 v124, v124
	v_rcp_f32_e32 v125, v125
	v_pk_fma_f32 v[106:107], v[190:191], v[110:111], v[106:107]
	v_pk_mul_f32 v[114:115], v[58:59], v[236:237]
	v_pk_add_f32 v[106:107], v[180:181], v[106:107]
	v_pk_mul_f32 v[108:109], v[108:109], v[124:125]
	v_mov_b32_dpp v123, v126 row_ror:15 row_mask:0xf bank_mask:0xf
	v_pk_mul_f32 v[106:107], v[106:107], v[108:109]
	v_pk_fma_f32 v[108:109], v[232:233], v[118:119], v[114:115]
	v_cvt_pk_bf16_f32 v106, v106, v107
	v_pk_fma_f32 v[108:109], v[240:241], v[122:123], v[108:109]
	v_pk_mul_f32 v[126:127], v[62:63], v[248:249]
	v_pk_add_f32 v[108:109], v[244:245], v[108:109]
	v_pk_fma_f32 v[114:115], v[252:253], v[116:117], v[126:127]
	v_mul_f32_e32 v110, 0xbfb8aa3b, v108
	v_exp_f32_e32 v110, v110
	v_mul_f32_e32 v111, 0xbfb8aa3b, v109
	v_exp_f32_e32 v111, v111
	v_pk_fma_f32 v[114:115], v[192:193], v[120:121], v[114:115]
	v_add_f32_e32 v107, 1.0, v110
	v_rcp_f32_e32 v110, v107
	v_add_f32_e32 v107, 1.0, v111
	v_rcp_f32_e32 v111, v107
	v_pk_add_f32 v[114:115], v[182:183], v[114:115]
	v_pk_mul_f32 v[116:117], v[48:49], v[234:235]
	v_cndmask_b32_e64 v118, v51, v43, s[6:7]
	v_pk_mul_f32 v[108:109], v[108:109], v[110:111]
	v_cndmask_b32_e64 v110, v49, v41, s[6:7]
	v_pk_mul_f32 v[108:109], v[114:115], v[108:109]
	v_cndmask_b32_e64 v111, v54, v46, s[6:7]
	v_cvt_pk_bf16_f32 v107, v108, v109
	global_store_dwordx2 v[168:169], v[106:107], off offset:32
	v_cndmask_b32_e64 v106, v52, v60, s[4:5]
	v_cndmask_b32_e64 v107, v52, v44, s[6:7]
	s_nop 0
; __device__ __forceinline__ void st_bf4(bf16_t* p, f32x4 v) { u32x2 w; w.x = pk2(v[0], v[1]); w.y = pk2(v[2], v[3]); *(u32x2*)p = w; }
; __device__ __forceinline__ float sigmoidf_(float x) { return __builtin_amdgcn_rcpf(1.f + __expf(-x)); }
; __device__ __forceinline__ float dpp_ror1(float v) { return __int_as_float(__builtin_amdgcn_update_dpp(0, __float_as_int(v), 0x121, 0xf, 0xf, false)); }
; __device__ __forceinline__ float dpp_rol1(float v) { return __int_as_float(__builtin_amdgcn_update_dpp(0, __float_as_int(v), 0x12F, 0xf, 0xf, false)); }
;     __device__ __forceinline__ void tile(const f32x4 (&acc)[2][2][4][2], const Unit& u, int wr, int wc, int fr, int fq) const {
;     ...
;                     for (int i = 0; i < 4; ++i) {
;                         const float xv = acc[ai][0][m][n][i], xg = acc[ai][1][m][n][i];
;                         const float uv = m > 0 ? acc[ai][0][m > 0 ? m - 1 : 0][n][i] : 0.f, ug = m > 0 ? acc[ai][1][m > 0 ? m - 1 : 0][n][i] : 0.f;
;                         const float dv = m < 3 ? acc[ai][0][m < 3 ? m + 1 : 3][n][i] : 0.f, dg = m < 3 ? acc[ai][1][m < 3 ? m + 1 : 3][n][i] : 0.f;
;                         const float pv = dpp_ror1(fr == 15 ? uv : xv), pg = dpp_ror1(fr == 15 ? ug : xg);
;                         const float nv = dpp_rol1(fr == 0 ? dv : xv), ng = dpp_rol1(fr == 0 ? dg : xg);
;                         const float yv = wv0[i] * pv + wv1[i] * xv + wv2[i] * nv + bv[i];
;                         const float yg = wg0[i] * pg + wg1[i] * xg + wg2[i] * ng + bg[i];
;                         r[i] = yg * sigmoidf_(yg) * yv;
;                     }
;                     st_bf4(ACT + (size_t)(u.pm * BM + ai * HALF + wr * 64 + m * 16 + fr) * FF + cv, r);
	v_mov_b32_dpp v60, v106 row_ror:1 row_mask:0xf bank_mask:0xf
	v_cndmask_b32_e64 v106, v48, v56, s[4:5]
	v_cndmask_b32_e64 v109, v53, v45, s[6:7]
	s_nop 0
	v_mov_b32_dpp v56, v106 row_ror:1 row_mask:0xf bank_mask:0xf
	v_cndmask_b32_e64 v115, v55, v47, s[6:7]
	v_pk_mul_f32 v[120:121], v[52:53], v[246:247]
	v_mov_b32_dpp v106, v107 row_ror:15 row_mask:0xf bank_mask:0xf
	v_cndmask_b32_e64 v107, v48, v40, s[6:7]
	s_nop 1
	v_mov_b32_dpp v108, v107 row_ror:15 row_mask:0xf bank_mask:0xf
	v_cndmask_b32_e64 v107, v53, v61, s[4:5]
	s_nop 1
	v_mov_b32_dpp v61, v107 row_ror:1 row_mask:0xf bank_mask:0xf
	v_cndmask_b32_e64 v107, v49, v57, s[4:5]
	v_pk_fma_f32 v[60:61], v[250:251], v[60:61], v[120:121]
	s_nop 0
	v_mov_b32_dpp v57, v107 row_ror:1 row_mask:0xf bank_mask:0xf
	v_pk_fma_f32 v[56:57], v[230:231], v[56:57], v[116:117]
	s_nop 0
	v_mov_b32_dpp v107, v109 row_ror:15 row_mask:0xf bank_mask:0xf
	v_pk_fma_f32 v[60:61], v[190:191], v[106:107], v[60:61]
	v_pk_mul_f32 v[106:107], v[40:41], v[234:235]
	v_mov_b32_dpp v109, v110 row_ror:15 row_mask:0xf bank_mask:0xf
	v_pk_fma_f32 v[56:57], v[238:239], v[108:109], v[56:57]
	v_cndmask_b32_e64 v110, v54, v62, s[4:5]
	v_pk_add_f32 v[56:57], v[242:243], v[56:57]
	s_nop 0
	v_mul_f32_e32 v108, 0xbfb8aa3b, v56
	v_mul_f32_e32 v117, 0xbfb8aa3b, v57
	v_mov_b32_dpp v62, v110 row_ror:1 row_mask:0xf bank_mask:0xf
	v_cndmask_b32_e64 v110, v50, v58, s[4:5]
	v_exp_f32_e32 v116, v108
	v_exp_f32_e32 v117, v117
	v_mov_b32_dpp v58, v110 row_ror:1 row_mask:0xf bank_mask:0xf
	v_add_f32_e32 v116, 1.0, v116
	v_add_f32_e32 v117, 1.0, v117
	v_mov_b32_dpp v110, v111 row_ror:15 row_mask:0xf bank_mask:0xf
	v_cndmask_b32_e64 v111, v50, v42, s[6:7]
	v_rcp_f32_e32 v116, v116
	v_rcp_f32_e32 v117, v117
	v_mov_b32_dpp v114, v111 row_ror:15 row_mask:0xf bank_mask:0xf
	v_cndmask_b32_e64 v111, v55, v63, s[4:5]
	v_pk_mul_f32 v[108:109], v[50:51], v[236:237]
	v_pk_add_f32 v[60:61], v[180:181], v[60:61]
	v_mov_b32_dpp v63, v111 row_ror:1 row_mask:0xf bank_mask:0xf
	v_cndmask_b32_e64 v111, v51, v59, s[4:5]
	v_pk_mul_f32 v[56:57], v[56:57], v[116:117]
	s_nop 0
	v_mov_b32_dpp v59, v111 row_ror:1 row_mask:0xf bank_mask:0xf
	v_pk_fma_f32 v[58:59], v[232:233], v[58:59], v[108:109]
	v_pk_mul_f32 v[56:57], v[60:61], v[56:57]
	v_mov_b32_dpp v111, v115 row_ror:15 row_mask:0xf bank_mask:0xf
	v_cvt_pk_bf16_f32 v56, v56, v57
	v_cndmask_b32_e64 v108, v43, v35, s[6:7]
	v_mov_b32_dpp v115, v118 row_ror:15 row_mask:0xf bank_mask:0xf
	v_pk_fma_f32 v[58:59], v[240:241], v[114:115], v[58:59]
	v_pk_mul_f32 v[118:119], v[54:55], v[248:249]
	v_pk_add_f32 v[58:59], v[244:245], v[58:59]
	v_pk_fma_f32 v[62:63], v[252:253], v[62:63], v[118:119]
	v_mul_f32_e32 v60, 0xbfb8aa3b, v58
	v_exp_f32_e32 v60, v60
	v_mul_f32_e32 v61, 0xbfb8aa3b, v59
	v_exp_f32_e32 v61, v61
	v_pk_fma_f32 v[62:63], v[192:193], v[110:111], v[62:63]
	v_add_f32_e32 v57, 1.0, v60
	v_rcp_f32_e32 v60, v57
	v_add_f32_e32 v57, 1.0, v61
	v_rcp_f32_e32 v61, v57
	v_pk_add_f32 v[62:63], v[182:183], v[62:63]
	v_pk_mul_f32 v[110:111], v[44:45], v[246:247]
	v_pk_mul_f32 v[58:59], v[58:59], v[60:61]
	s_nop 0
	v_pk_mul_f32 v[58:59], v[62:63], v[58:59]
	v_cndmask_b32_e64 v60, v41, v33, s[6:7]
	v_cvt_pk_bf16_f32 v57, v58, v59
	global_store_dwordx2 v[152:153], v[56:57], off offset:32
	v_cndmask_b32_e64 v56, v44, v52, s[4:5]
	v_cndmask_b32_e64 v57, v44, v36, s[6:7]
	s_nop 0
	v_mov_b32_dpp v52, v56 row_ror:1 row_mask:0xf bank_mask:0xf
	v_cndmask_b32_e64 v56, v40, v48, s[4:5]
	v_cndmask_b32_e64 v59, v45, v37, s[6:7]
	v_cndmask_b32_e64 v61, v46, v38, s[6:7]
	v_mov_b32_dpp v48, v56 row_ror:1 row_mask:0xf bank_mask:0xf
	v_cndmask_b32_e64 v63, v47, v39, s[6:7]
	v_mov_b32_dpp v56, v57 row_ror:15 row_mask:0xf bank_mask:0xf
	v_cndmask_b32_e64 v57, v40, v32, s[6:7]
	s_nop 1
	v_mov_b32_dpp v58, v57 row_ror:15 row_mask:0xf bank_mask:0xf
	v_cndmask_b32_e64 v57, v45, v53, s[4:5]
	s_nop 1
	v_mov_b32_dpp v53, v57 row_ror:1 row_mask:0xf bank_mask:0xf
	v_cndmask_b32_e64 v57, v41, v49, s[4:5]
	v_pk_fma_f32 v[52:53], v[250:251], v[52:53], v[110:111]
	s_nop 0
	v_mov_b32_dpp v49, v57 row_ror:1 row_mask:0xf bank_mask:0xf
	v_pk_fma_f32 v[48:49], v[230:231], v[48:49], v[106:107]
	s_nop 0
	v_mov_b32_dpp v57, v59 row_ror:15 row_mask:0xf bank_mask:0xf
	v_pk_fma_f32 v[52:53], v[190:191], v[56:57], v[52:53]
	v_cndmask_b32_e64 v56, v35, 0, s[6:7]
	v_mov_b32_dpp v59, v60 row_ror:15 row_mask:0xf bank_mask:0xf
	v_pk_fma_f32 v[48:49], v[238:239], v[58:59], v[48:49]
	v_cndmask_b32_e64 v60, v46, v54, s[4:5]
	v_pk_add_f32 v[48:49], v[242:243], v[48:49]
	s_nop 0
	v_mul_f32_e32 v58, 0xbfb8aa3b, v48
	v_mul_f32_e32 v107, 0xbfb8aa3b, v49
	v_mov_b32_dpp v54, v60 row_ror:1 row_mask:0xf bank_mask:0xf
	v_cndmask_b32_e64 v60, v42, v50, s[4:5]
	v_exp_f32_e32 v106, v58
	v_exp_f32_e32 v107, v107
	v_mov_b32_dpp v50, v60 row_ror:1 row_mask:0xf bank_mask:0xf
	v_add_f32_e32 v106, 1.0, v106
	v_add_f32_e32 v107, 1.0, v107
	v_mov_b32_dpp v60, v61 row_ror:15 row_mask:0xf bank_mask:0xf
	v_cndmask_b32_e64 v61, v42, v34, s[6:7]
	v_rcp_f32_e32 v106, v106
	v_rcp_f32_e32 v107, v107
	v_mov_b32_dpp v62, v61 row_ror:15 row_mask:0xf bank_mask:0xf
	v_cndmask_b32_e64 v61, v47, v55, s[4:5]
	v_pk_mul_f32 v[58:59], v[42:43], v[236:237]
	v_pk_add_f32 v[52:53], v[180:181], v[52:53]
	v_mov_b32_dpp v55, v61 row_ror:1 row_mask:0xf bank_mask:0xf
	v_cndmask_b32_e64 v61, v43, v51, s[4:5]
	v_pk_mul_f32 v[48:49], v[48:49], v[106:107]
	s_nop 0
	v_mov_b32_dpp v51, v61 row_ror:1 row_mask:0xf bank_mask:0xf
	v_pk_fma_f32 v[50:51], v[232:233], v[50:51], v[58:59]
	v_pk_mul_f32 v[48:49], v[52:53], v[48:49]
	v_mov_b32_dpp v61, v63 row_ror:15 row_mask:0xf bank_mask:0xf
	v_cvt_pk_bf16_f32 v48, v48, v49
	s_nop 0
; __device__ __forceinline__ void st_bf4(bf16_t* p, f32x4 v) { u32x2 w; w.x = pk2(v[0], v[1]); w.y = pk2(v[2], v[3]); *(u32x2*)p = w; }
; __device__ __forceinline__ float sigmoidf_(float x) { return __builtin_amdgcn_rcpf(1.f + __expf(-x)); }
; __device__ __forceinline__ float dpp_ror1(float v) { return __int_as_float(__builtin_amdgcn_update_dpp(0, __float_as_int(v), 0x121, 0xf, 0xf, false)); }
; __device__ __forceinline__ float dpp_rol1(float v) { return __int_as_float(__builtin_amdgcn_update_dpp(0, __float_as_int(v), 0x12F, 0xf, 0xf, false)); }
;     __device__ __forceinline__ void tile(const f32x4 (&acc)[2][2][4][2], const Unit& u, int wr, int wc, int fr, int fq) const {
;     ...
;                     for (int i = 0; i < 4; ++i) {
;                         const float xv = acc[ai][0][m][n][i], xg = acc[ai][1][m][n][i];
;                         const float uv = m > 0 ? acc[ai][0][m > 0 ? m - 1 : 0][n][i] : 0.f, ug = m > 0 ? acc[ai][1][m > 0 ? m - 1 : 0][n][i] : 0.f;
;                         const float dv = m < 3 ? acc[ai][0][m < 3 ? m + 1 : 3][n][i] : 0.f, dg = m < 3 ? acc[ai][1][m < 3 ? m + 1 : 3][n][i] : 0.f;
;                         const float pv = dpp_ror1(fr == 15 ? uv : xv), pg = dpp_ror1(fr == 15 ? ug : xg);
;                         const float nv = dpp_rol1(fr == 0 ? dv : xv), ng = dpp_rol1(fr == 0 ? dg : xg);
;                         const float yv = wv0[i] * pv + wv1[i] * xv + wv2[i] * nv + bv[i];
;                         const float yg = wg0[i] * pg + wg1[i] * xg + wg2[i] * ng + bg[i];
;                         r[i] = yg * sigmoidf_(yg) * yv;
;                     }
;                     st_bf4(ACT + (size_t)(u.pm * BM + ai * HALF + wr * 64 + m * 16 + fr) * FF + cv, r);
	v_mov_b32_dpp v63, v108 row_ror:15 row_mask:0xf bank_mask:0xf
	v_pk_fma_f32 v[50:51], v[240:241], v[62:63], v[50:51]
	v_pk_mul_f32 v[108:109], v[46:47], v[248:249]
	v_pk_add_f32 v[50:51], v[244:245], v[50:51]
	v_pk_fma_f32 v[54:55], v[252:253], v[54:55], v[108:109]
	v_mul_f32_e32 v52, 0xbfb8aa3b, v50
	v_exp_f32_e32 v52, v52
	v_mul_f32_e32 v53, 0xbfb8aa3b, v51
	v_exp_f32_e32 v53, v53
	v_pk_fma_f32 v[54:55], v[192:193], v[60:61], v[54:55]
	v_add_f32_e32 v49, 1.0, v52
	v_rcp_f32_e32 v52, v49
	v_add_f32_e32 v49, 1.0, v53
	v_rcp_f32_e32 v53, v49
	v_pk_add_f32 v[54:55], v[182:183], v[54:55]
	v_pk_mul_f32 v[50:51], v[50:51], v[52:53]
	s_nop 0
	v_pk_mul_f32 v[50:51], v[54:55], v[50:51]
	v_cndmask_b32_e64 v52, v33, 0, s[6:7]
	v_cvt_pk_bf16_f32 v49, v50, v51
	global_store_dwordx2 v[112:113], v[48:49], off offset:32
	v_cndmask_b32_e64 v48, v36, v44, s[4:5]
	v_cndmask_b32_e64 v49, v36, 0, s[6:7]
	s_nop 0
	v_mov_b32_dpp v44, v48 row_ror:1 row_mask:0xf bank_mask:0xf
	v_cndmask_b32_e64 v48, v32, v40, s[4:5]
	v_cndmask_b32_e64 v51, v37, 0, s[6:7]
	v_cndmask_b32_e64 v53, v38, 0, s[6:7]
	v_mov_b32_dpp v40, v48 row_ror:1 row_mask:0xf bank_mask:0xf
	v_cndmask_b32_e64 v55, v39, 0, s[6:7]
	v_mov_b32_dpp v48, v49 row_ror:15 row_mask:0xf bank_mask:0xf
	v_cndmask_b32_e64 v49, v32, 0, s[6:7]
	s_nop 1
	v_mov_b32_dpp v50, v49 row_ror:15 row_mask:0xf bank_mask:0xf
	v_cndmask_b32_e64 v49, v37, v45, s[4:5]
	v_pk_mul_f32 v[36:37], v[36:37], v[246:247]
	s_nop 0
	v_mov_b32_dpp v45, v49 row_ror:1 row_mask:0xf bank_mask:0xf
	v_cndmask_b32_e64 v49, v33, v41, s[4:5]
	v_pk_mul_f32 v[32:33], v[32:33], v[234:235]
	v_pk_fma_f32 v[36:37], v[250:251], v[44:45], v[36:37]
	v_mov_b32_dpp v41, v49 row_ror:1 row_mask:0xf bank_mask:0xf
	v_pk_fma_f32 v[32:33], v[230:231], v[40:41], v[32:33]
	v_mov_b32_dpp v49, v51 row_ror:15 row_mask:0xf bank_mask:0xf
	v_pk_fma_f32 v[36:37], v[190:191], v[48:49], v[36:37]
	v_pk_mul_f32 v[48:49], v[24:25], v[234:235]
	v_mov_b32_dpp v51, v52 row_ror:15 row_mask:0xf bank_mask:0xf
	v_pk_fma_f32 v[32:33], v[238:239], v[50:51], v[32:33]
	v_cndmask_b32_e64 v52, v38, v46, s[4:5]
	v_pk_add_f32 v[32:33], v[242:243], v[32:33]
	s_nop 0
	v_mul_f32_e32 v40, 0xbfb8aa3b, v32
	v_mul_f32_e32 v41, 0xbfb8aa3b, v33
	v_mov_b32_dpp v46, v52 row_ror:1 row_mask:0xf bank_mask:0xf
	v_cndmask_b32_e64 v52, v34, v42, s[4:5]
	v_exp_f32_e32 v40, v40
	v_exp_f32_e32 v41, v41
	v_mov_b32_dpp v42, v52 row_ror:1 row_mask:0xf bank_mask:0xf
	v_add_f32_e32 v40, 1.0, v40
	v_add_f32_e32 v41, 1.0, v41
	v_mov_b32_dpp v52, v53 row_ror:15 row_mask:0xf bank_mask:0xf
	v_cndmask_b32_e64 v53, v34, 0, s[6:7]
	v_rcp_f32_e32 v40, v40
	v_rcp_f32_e32 v41, v41
	v_mov_b32_dpp v54, v53 row_ror:15 row_mask:0xf bank_mask:0xf
	v_cndmask_b32_e64 v53, v39, v47, s[4:5]
	v_pk_add_f32 v[36:37], v[180:181], v[36:37]
	v_pk_mul_f32 v[32:33], v[32:33], v[40:41]
	v_mov_b32_dpp v47, v53 row_ror:1 row_mask:0xf bank_mask:0xf
	v_cndmask_b32_e64 v53, v35, v43, s[4:5]
	v_pk_mul_f32 v[34:35], v[34:35], v[236:237]
	v_pk_mul_f32 v[32:33], v[36:37], v[32:33]
	v_mov_b32_dpp v43, v53 row_ror:1 row_mask:0xf bank_mask:0xf
	v_pk_fma_f32 v[34:35], v[232:233], v[42:43], v[34:35]
	v_cvt_pk_bf16_f32 v32, v32, v33
	v_mov_b32_dpp v53, v55 row_ror:15 row_mask:0xf bank_mask:0xf
	v_pk_mul_f32 v[38:39], v[38:39], v[248:249]
	v_cndmask_b32_e64 v40, v25, v17, s[6:7]
	v_mov_b32_dpp v55, v56 row_ror:15 row_mask:0xf bank_mask:0xf
	v_pk_fma_f32 v[34:35], v[240:241], v[54:55], v[34:35]
	v_pk_fma_f32 v[38:39], v[252:253], v[46:47], v[38:39]
	v_pk_add_f32 v[34:35], v[244:245], v[34:35]
	v_pk_fma_f32 v[38:39], v[192:193], v[52:53], v[38:39]
	v_mul_f32_e32 v36, 0xbfb8aa3b, v34
	v_exp_f32_e32 v36, v36
	v_mul_f32_e32 v37, 0xbfb8aa3b, v35
	v_exp_f32_e32 v37, v37
	v_pk_add_f32 v[38:39], v[182:183], v[38:39]
	v_add_f32_e32 v33, 1.0, v36
	v_rcp_f32_e32 v36, v33
	v_add_f32_e32 v33, 1.0, v37
	v_rcp_f32_e32 v37, v33
	v_cndmask_b32_e64 v41, v30, 0, s[4:5]
	v_pk_mul_f32 v[34:35], v[34:35], v[36:37]
	s_nop 0
	v_pk_mul_f32 v[34:35], v[38:39], v[34:35]
	s_nop 0
	v_cvt_pk_bf16_f32 v33, v34, v35
	global_store_dwordx2 v[96:97], v[32:33], off offset:32
	v_cndmask_b32_e64 v33, v28, 0, s[4:5]
	v_cndmask_b32_e64 v35, v29, 0, s[4:5]
	s_nop 0
	v_mov_b32_dpp v32, v33 row_ror:1 row_mask:0xf bank_mask:0xf
	v_cndmask_b32_e64 v33, v24, 0, s[4:5]
	v_cndmask_b32_e64 v37, v25, 0, s[4:5]
	v_cndmask_b32_e64 v39, v29, v21, s[6:7]
	v_mov_b32_dpp v34, v33 row_ror:1 row_mask:0xf bank_mask:0xf
	v_cndmask_b32_e64 v33, v28, v20, s[6:7]
	v_cndmask_b32_e64 v43, v31, 0, s[4:5]
	v_pk_mul_f32 v[52:53], v[28:29], v[246:247]
	v_mov_b32_dpp v36, v33 row_ror:15 row_mask:0xf bank_mask:0xf
	v_cndmask_b32_e64 v33, v24, v16, s[6:7]
	v_cndmask_b32_e64 v45, v27, 0, s[4:5]
	v_cndmask_b32_e64 v47, v31, v23, s[6:7]
	v_mov_b32_dpp v38, v33 row_ror:15 row_mask:0xf bank_mask:0xf
	v_cndmask_b32_e64 v50, v27, v19, s[6:7]
	s_nop 0
	v_mov_b32_dpp v33, v35 row_ror:1 row_mask:0xf bank_mask:0xf
	v_pk_fma_f32 v[32:33], v[250:251], v[32:33], v[52:53]
	s_nop 0
	v_mov_b32_dpp v35, v37 row_ror:1 row_mask:0xf bank_mask:0xf
	v_pk_fma_f32 v[34:35], v[230:231], v[34:35], v[48:49]
	s_nop 0
	v_mov_b32_dpp v37, v39 row_ror:15 row_mask:0xf bank_mask:0xf
	v_pk_fma_f32 v[32:33], v[190:191], v[36:37], v[32:33]
	s_nop 0
	v_mov_b32_dpp v39, v40 row_ror:15 row_mask:0xf bank_mask:0xf
	v_pk_fma_f32 v[34:35], v[238:239], v[38:39], v[34:35]
	s_nop 0
	v_pk_add_f32 v[34:35], v[242:243], v[34:35]
	v_pk_add_f32 v[32:33], v[180:181], v[32:33]
	v_mul_f32_e32 v38, 0xbfb8aa3b, v34
	v_mul_f32_e32 v49, 0xbfb8aa3b, v35
	v_exp_f32_e32 v48, v38
	v_exp_f32_e32 v49, v49
	v_mov_b32_dpp v40, v41 row_ror:1 row_mask:0xf bank_mask:0xf
	v_cndmask_b32_e64 v41, v26, 0, s[4:5]
; __device__ __forceinline__ void st_bf4(bf16_t* p, f32x4 v) { u32x2 w; w.x = pk2(v[0], v[1]); w.y = pk2(v[2], v[3]); *(u32x2*)p = w; }
; __device__ __forceinline__ float sigmoidf_(float x) { return __builtin_amdgcn_rcpf(1.f + __expf(-x)); }
; __device__ __forceinline__ float dpp_ror1(float v) { return __int_as_float(__builtin_amdgcn_update_dpp(0, __float_as_int(v), 0x121, 0xf, 0xf, false)); }
; __device__ __forceinline__ float dpp_rol1(float v) { return __int_as_float(__builtin_amdgcn_update_dpp(0, __float_as_int(v), 0x12F, 0xf, 0xf, false)); }
;     __device__ __forceinline__ void tile(const f32x4 (&acc)[2][2][4][2], const Unit& u, int wr, int wc, int fr, int fq) const {
;     ...
;                     for (int i = 0; i < 4; ++i) {
;                         const float xv = acc[ai][0][m][n][i], xg = acc[ai][1][m][n][i];
;                         const float uv = m > 0 ? acc[ai][0][m > 0 ? m - 1 : 0][n][i] : 0.f, ug = m > 0 ? acc[ai][1][m > 0 ? m - 1 : 0][n][i] : 0.f;
;                         const float dv = m < 3 ? acc[ai][0][m < 3 ? m + 1 : 3][n][i] : 0.f, dg = m < 3 ? acc[ai][1][m < 3 ? m + 1 : 3][n][i] : 0.f;
;                         const float pv = dpp_ror1(fr == 15 ? uv : xv), pg = dpp_ror1(fr == 15 ? ug : xg);
;                         const float nv = dpp_rol1(fr == 0 ? dv : xv), ng = dpp_rol1(fr == 0 ? dg : xg);
;                         const float yv = wv0[i] * pv + wv1[i] * xv + wv2[i] * nv + bv[i];
;                         const float yg = wg0[i] * pg + wg1[i] * xg + wg2[i] * ng + bg[i];
;                         r[i] = yg * sigmoidf_(yg) * yv;
;                     }
;                     st_bf4(ACT + (size_t)(u.pm * BM + ai * HALF + wr * 64 + m * 16 + fr) * FF + cv, r);
	v_add_f32_e32 v48, 1.0, v48
	v_add_f32_e32 v49, 1.0, v49
	v_mov_b32_dpp v42, v41 row_ror:1 row_mask:0xf bank_mask:0xf
	v_cndmask_b32_e64 v41, v30, v22, s[6:7]
	v_rcp_f32_e32 v48, v48
	v_rcp_f32_e32 v49, v49
	v_mov_b32_dpp v44, v41 row_ror:15 row_mask:0xf bank_mask:0xf
	v_cndmask_b32_e64 v41, v26, v18, s[6:7]
	v_pk_mul_f32 v[38:39], v[26:27], v[236:237]
	v_pk_mul_f32 v[34:35], v[34:35], v[48:49]
	v_mov_b32_dpp v46, v41 row_ror:15 row_mask:0xf bank_mask:0xf
	v_pk_mul_f32 v[32:33], v[32:33], v[34:35]
	s_nop 0
	v_mov_b32_dpp v41, v43 row_ror:1 row_mask:0xf bank_mask:0xf
	v_cvt_pk_bf16_f32 v32, v32, v33
	s_nop 0
	v_mov_b32_dpp v43, v45 row_ror:1 row_mask:0xf bank_mask:0xf
	v_pk_fma_f32 v[34:35], v[232:233], v[42:43], v[38:39]
	v_cndmask_b32_e64 v42, v19, v11, s[6:7]
	v_mov_b32_dpp v45, v47 row_ror:15 row_mask:0xf bank_mask:0xf
	s_nop 1
	v_mov_b32_dpp v47, v50 row_ror:15 row_mask:0xf bank_mask:0xf
	v_pk_fma_f32 v[34:35], v[240:241], v[46:47], v[34:35]
	v_pk_mul_f32 v[50:51], v[30:31], v[248:249]
	v_pk_add_f32 v[34:35], v[244:245], v[34:35]
	v_pk_fma_f32 v[38:39], v[252:253], v[40:41], v[50:51]
	v_mul_f32_e32 v36, 0xbfb8aa3b, v34
	v_exp_f32_e32 v36, v36
	v_mul_f32_e32 v37, 0xbfb8aa3b, v35
	v_exp_f32_e32 v37, v37
	v_pk_fma_f32 v[38:39], v[192:193], v[44:45], v[38:39]
	v_add_f32_e32 v33, 1.0, v36
	v_rcp_f32_e32 v36, v33
	v_add_f32_e32 v33, 1.0, v37
	v_rcp_f32_e32 v37, v33
	v_pk_add_f32 v[38:39], v[182:183], v[38:39]
	v_pk_mul_f32 v[40:41], v[16:17], v[234:235]
	v_pk_mul_f32 v[44:45], v[20:21], v[246:247]
	v_pk_mul_f32 v[34:35], v[34:35], v[36:37]
	v_cndmask_b32_e64 v36, v17, v9, s[6:7]
	v_pk_mul_f32 v[34:35], v[38:39], v[34:35]
	v_cndmask_b32_e64 v37, v22, v14, s[6:7]
	v_cvt_pk_bf16_f32 v33, v34, v35
	global_store_dwordx2 v[98:99], v[32:33], off offset:32
	v_cndmask_b32_e64 v32, v20, v28, s[4:5]
	v_cndmask_b32_e64 v33, v20, v12, s[6:7]
	s_nop 0
	v_mov_b32_dpp v28, v32 row_ror:1 row_mask:0xf bank_mask:0xf
	v_cndmask_b32_e64 v32, v16, v24, s[4:5]
	v_cndmask_b32_e64 v35, v21, v13, s[6:7]
	s_nop 0
	v_mov_b32_dpp v24, v32 row_ror:1 row_mask:0xf bank_mask:0xf
	v_cndmask_b32_e64 v39, v23, v15, s[6:7]
	s_nop 0
	v_mov_b32_dpp v32, v33 row_ror:15 row_mask:0xf bank_mask:0xf
	v_cndmask_b32_e64 v33, v16, v8, s[6:7]
	s_nop 1
	v_mov_b32_dpp v34, v33 row_ror:15 row_mask:0xf bank_mask:0xf
	v_cndmask_b32_e64 v33, v21, v29, s[4:5]
	s_nop 1
	v_mov_b32_dpp v29, v33 row_ror:1 row_mask:0xf bank_mask:0xf
	v_cndmask_b32_e64 v33, v17, v25, s[4:5]
	v_pk_fma_f32 v[28:29], v[250:251], v[28:29], v[44:45]
	s_nop 0
	v_mov_b32_dpp v25, v33 row_ror:1 row_mask:0xf bank_mask:0xf
	v_pk_fma_f32 v[24:25], v[230:231], v[24:25], v[40:41]
	s_nop 0
	v_mov_b32_dpp v33, v35 row_ror:15 row_mask:0xf bank_mask:0xf
	v_pk_fma_f32 v[28:29], v[190:191], v[32:33], v[28:29]
	v_pk_mul_f32 v[32:33], v[8:9], v[234:235]
	v_mov_b32_dpp v35, v36 row_ror:15 row_mask:0xf bank_mask:0xf
	v_pk_fma_f32 v[24:25], v[238:239], v[34:35], v[24:25]
	v_cndmask_b32_e64 v36, v22, v30, s[4:5]
	v_pk_add_f32 v[24:25], v[242:243], v[24:25]
	s_nop 0
	v_mul_f32_e32 v34, 0xbfb8aa3b, v24
	v_mul_f32_e32 v41, 0xbfb8aa3b, v25
	v_mov_b32_dpp v30, v36 row_ror:1 row_mask:0xf bank_mask:0xf
	v_cndmask_b32_e64 v36, v18, v26, s[4:5]
	v_exp_f32_e32 v40, v34
	v_exp_f32_e32 v41, v41
	v_mov_b32_dpp v26, v36 row_ror:1 row_mask:0xf bank_mask:0xf
	v_add_f32_e32 v40, 1.0, v40
	v_add_f32_e32 v41, 1.0, v41
	v_mov_b32_dpp v36, v37 row_ror:15 row_mask:0xf bank_mask:0xf
	v_cndmask_b32_e64 v37, v18, v10, s[6:7]
	v_rcp_f32_e32 v40, v40
	v_rcp_f32_e32 v41, v41
	v_mov_b32_dpp v38, v37 row_ror:15 row_mask:0xf bank_mask:0xf
	v_cndmask_b32_e64 v37, v23, v31, s[4:5]
	v_pk_mul_f32 v[34:35], v[18:19], v[236:237]
	v_pk_add_f32 v[28:29], v[180:181], v[28:29]
	v_mov_b32_dpp v31, v37 row_ror:1 row_mask:0xf bank_mask:0xf
	v_cndmask_b32_e64 v37, v19, v27, s[4:5]
	v_pk_mul_f32 v[24:25], v[24:25], v[40:41]
	s_nop 0
	v_mov_b32_dpp v27, v37 row_ror:1 row_mask:0xf bank_mask:0xf
	v_pk_fma_f32 v[26:27], v[232:233], v[26:27], v[34:35]
	v_pk_mul_f32 v[24:25], v[28:29], v[24:25]
	v_mov_b32_dpp v37, v39 row_ror:15 row_mask:0xf bank_mask:0xf
	v_cvt_pk_bf16_f32 v24, v24, v25
	v_cndmask_b32_e64 v34, v11, v3, s[6:7]
	v_mov_b32_dpp v39, v42 row_ror:15 row_mask:0xf bank_mask:0xf
	v_pk_fma_f32 v[26:27], v[240:241], v[38:39], v[26:27]
	v_pk_mul_f32 v[42:43], v[22:23], v[248:249]
	v_pk_add_f32 v[26:27], v[244:245], v[26:27]
	v_pk_fma_f32 v[30:31], v[252:253], v[30:31], v[42:43]
	v_mul_f32_e32 v28, 0xbfb8aa3b, v26
	v_exp_f32_e32 v28, v28
	v_mul_f32_e32 v29, 0xbfb8aa3b, v27
	v_exp_f32_e32 v29, v29
	v_pk_fma_f32 v[30:31], v[192:193], v[36:37], v[30:31]
	v_add_f32_e32 v25, 1.0, v28
	v_rcp_f32_e32 v28, v25
	v_add_f32_e32 v25, 1.0, v29
	v_rcp_f32_e32 v29, v25
	v_pk_add_f32 v[30:31], v[182:183], v[30:31]
	v_pk_mul_f32 v[36:37], v[12:13], v[246:247]
	v_pk_mul_f32 v[26:27], v[26:27], v[28:29]
	s_nop 0
	v_pk_mul_f32 v[26:27], v[30:31], v[26:27]
	v_cndmask_b32_e64 v28, v9, v1, s[6:7]
	v_cvt_pk_bf16_f32 v25, v26, v27
	global_store_dwordx2 v[100:101], v[24:25], off offset:32
	v_cndmask_b32_e64 v24, v12, v20, s[4:5]
	v_cndmask_b32_e64 v25, v12, v4, s[6:7]
	s_nop 0
	v_mov_b32_dpp v20, v24 row_ror:1 row_mask:0xf bank_mask:0xf
	v_cndmask_b32_e64 v24, v8, v16, s[4:5]
	v_cndmask_b32_e64 v27, v13, v5, s[6:7]
	v_cndmask_b32_e64 v29, v14, v6, s[6:7]
	v_mov_b32_dpp v16, v24 row_ror:1 row_mask:0xf bank_mask:0xf
	v_cndmask_b32_e64 v31, v15, v7, s[6:7]
	v_mov_b32_dpp v24, v25 row_ror:15 row_mask:0xf bank_mask:0xf
	v_cndmask_b32_e64 v25, v8, v0, s[6:7]
	s_nop 1
	v_mov_b32_dpp v26, v25 row_ror:15 row_mask:0xf bank_mask:0xf
	v_cndmask_b32_e64 v25, v13, v21, s[4:5]
	s_nop 1
	v_mov_b32_dpp v21, v25 row_ror:1 row_mask:0xf bank_mask:0xf
; __device__ __forceinline__ void st_bf4(bf16_t* p, f32x4 v) { u32x2 w; w.x = pk2(v[0], v[1]); w.y = pk2(v[2], v[3]); *(u32x2*)p = w; }
; __device__ __forceinline__ float sigmoidf_(float x) { return __builtin_amdgcn_rcpf(1.f + __expf(-x)); }
; __device__ __forceinline__ float dpp_ror1(float v) { return __int_as_float(__builtin_amdgcn_update_dpp(0, __float_as_int(v), 0x121, 0xf, 0xf, false)); }
; __device__ __forceinline__ float dpp_rol1(float v) { return __int_as_float(__builtin_amdgcn_update_dpp(0, __float_as_int(v), 0x12F, 0xf, 0xf, false)); }
;     __device__ __forceinline__ void tile(const f32x4 (&acc)[2][2][4][2], const Unit& u, int wr, int wc, int fr, int fq) const {
;     ...
;                     for (int i = 0; i < 4; ++i) {
;                         const float xv = acc[ai][0][m][n][i], xg = acc[ai][1][m][n][i];
;                         const float uv = m > 0 ? acc[ai][0][m > 0 ? m - 1 : 0][n][i] : 0.f, ug = m > 0 ? acc[ai][1][m > 0 ? m - 1 : 0][n][i] : 0.f;
;                         const float dv = m < 3 ? acc[ai][0][m < 3 ? m + 1 : 3][n][i] : 0.f, dg = m < 3 ? acc[ai][1][m < 3 ? m + 1 : 3][n][i] : 0.f;
;                         const float pv = dpp_ror1(fr == 15 ? uv : xv), pg = dpp_ror1(fr == 15 ? ug : xg);
;                         const float nv = dpp_rol1(fr == 0 ? dv : xv), ng = dpp_rol1(fr == 0 ? dg : xg);
;                         const float yv = wv0[i] * pv + wv1[i] * xv + wv2[i] * nv + bv[i];
;                         const float yg = wg0[i] * pg + wg1[i] * xg + wg2[i] * ng + bg[i];
;                         r[i] = yg * sigmoidf_(yg) * yv;
;                     }
;                     st_bf4(ACT + (size_t)(u.pm * BM + ai * HALF + wr * 64 + m * 16 + fr) * FF + cv, r);
	v_cndmask_b32_e64 v25, v9, v17, s[4:5]
	v_pk_fma_f32 v[20:21], v[250:251], v[20:21], v[36:37]
	s_nop 0
	v_mov_b32_dpp v17, v25 row_ror:1 row_mask:0xf bank_mask:0xf
	v_pk_fma_f32 v[16:17], v[230:231], v[16:17], v[32:33]
	s_nop 0
	v_mov_b32_dpp v25, v27 row_ror:15 row_mask:0xf bank_mask:0xf
	v_pk_fma_f32 v[20:21], v[190:191], v[24:25], v[20:21]
	v_cndmask_b32_e64 v24, v3, 0, s[6:7]
	v_mov_b32_dpp v27, v28 row_ror:15 row_mask:0xf bank_mask:0xf
	v_pk_fma_f32 v[16:17], v[238:239], v[26:27], v[16:17]
	v_cndmask_b32_e64 v28, v14, v22, s[4:5]
	v_pk_add_f32 v[16:17], v[242:243], v[16:17]
	s_nop 0
	v_mul_f32_e32 v26, 0xbfb8aa3b, v16
	v_mul_f32_e32 v33, 0xbfb8aa3b, v17
	v_mov_b32_dpp v22, v28 row_ror:1 row_mask:0xf bank_mask:0xf
	v_cndmask_b32_e64 v28, v10, v18, s[4:5]
	v_exp_f32_e32 v32, v26
	v_exp_f32_e32 v33, v33
	v_mov_b32_dpp v18, v28 row_ror:1 row_mask:0xf bank_mask:0xf
	v_add_f32_e32 v32, 1.0, v32
	v_add_f32_e32 v33, 1.0, v33
	v_mov_b32_dpp v28, v29 row_ror:15 row_mask:0xf bank_mask:0xf
	v_cndmask_b32_e64 v29, v10, v2, s[6:7]
	v_rcp_f32_e32 v32, v32
	v_rcp_f32_e32 v33, v33
	v_mov_b32_dpp v30, v29 row_ror:15 row_mask:0xf bank_mask:0xf
	v_cndmask_b32_e64 v29, v15, v23, s[4:5]
	v_pk_mul_f32 v[26:27], v[10:11], v[236:237]
	v_pk_add_f32 v[20:21], v[180:181], v[20:21]
	v_mov_b32_dpp v23, v29 row_ror:1 row_mask:0xf bank_mask:0xf
	v_cndmask_b32_e64 v29, v11, v19, s[4:5]
	v_pk_mul_f32 v[16:17], v[16:17], v[32:33]
	s_nop 0
	v_mov_b32_dpp v19, v29 row_ror:1 row_mask:0xf bank_mask:0xf
	v_pk_fma_f32 v[18:19], v[232:233], v[18:19], v[26:27]
	v_pk_mul_f32 v[16:17], v[20:21], v[16:17]
	v_mov_b32_dpp v29, v31 row_ror:15 row_mask:0xf bank_mask:0xf
	v_cvt_pk_bf16_f32 v16, v16, v17
	s_nop 0
	v_mov_b32_dpp v31, v34 row_ror:15 row_mask:0xf bank_mask:0xf
	v_pk_fma_f32 v[18:19], v[240:241], v[30:31], v[18:19]
	v_pk_mul_f32 v[34:35], v[14:15], v[248:249]
	v_pk_add_f32 v[18:19], v[244:245], v[18:19]
	v_pk_fma_f32 v[22:23], v[252:253], v[22:23], v[34:35]
	v_mul_f32_e32 v20, 0xbfb8aa3b, v18
	v_exp_f32_e32 v20, v20
	v_mul_f32_e32 v21, 0xbfb8aa3b, v19
	v_exp_f32_e32 v21, v21
	v_pk_fma_f32 v[22:23], v[192:193], v[28:29], v[22:23]
	v_add_f32_e32 v17, 1.0, v20
	v_rcp_f32_e32 v20, v17
	v_add_f32_e32 v17, 1.0, v21
	v_rcp_f32_e32 v21, v17
	v_pk_add_f32 v[22:23], v[182:183], v[22:23]
	v_pk_mul_f32 v[18:19], v[18:19], v[20:21]
	s_nop 0
	v_pk_mul_f32 v[18:19], v[22:23], v[18:19]
	v_cndmask_b32_e64 v20, v1, 0, s[6:7]
	v_cvt_pk_bf16_f32 v17, v18, v19
	global_store_dwordx2 v[102:103], v[16:17], off offset:32
	v_cndmask_b32_e64 v16, v4, v12, s[4:5]
	v_cndmask_b32_e64 v17, v4, 0, s[6:7]
	s_nop 0
	v_mov_b32_dpp v12, v16 row_ror:1 row_mask:0xf bank_mask:0xf
	v_cndmask_b32_e64 v16, v0, v8, s[4:5]
	v_cndmask_b32_e64 v19, v5, 0, s[6:7]
	v_cndmask_b32_e64 v21, v6, 0, s[6:7]
	v_mov_b32_dpp v8, v16 row_ror:1 row_mask:0xf bank_mask:0xf
	v_cndmask_b32_e64 v23, v7, 0, s[6:7]
	v_mov_b32_dpp v16, v17 row_ror:15 row_mask:0xf bank_mask:0xf
	v_cndmask_b32_e64 v17, v0, 0, s[6:7]
	s_nop 1
	v_mov_b32_dpp v18, v17 row_ror:15 row_mask:0xf bank_mask:0xf
	v_cndmask_b32_e64 v17, v5, v13, s[4:5]
	v_pk_mul_f32 v[4:5], v[4:5], v[246:247]
	s_nop 0
	v_mov_b32_dpp v13, v17 row_ror:1 row_mask:0xf bank_mask:0xf
	v_cndmask_b32_e64 v17, v1, v9, s[4:5]
	v_pk_mul_f32 v[0:1], v[0:1], v[234:235]
	v_pk_fma_f32 v[4:5], v[250:251], v[12:13], v[4:5]
	v_mov_b32_dpp v9, v17 row_ror:1 row_mask:0xf bank_mask:0xf
	v_pk_fma_f32 v[0:1], v[230:231], v[8:9], v[0:1]
	s_nop 0
	v_mov_b32_dpp v17, v19 row_ror:15 row_mask:0xf bank_mask:0xf
	v_pk_fma_f32 v[4:5], v[190:191], v[16:17], v[4:5]
	s_nop 0
	v_mov_b32_dpp v19, v20 row_ror:15 row_mask:0xf bank_mask:0xf
	v_pk_fma_f32 v[0:1], v[238:239], v[18:19], v[0:1]
	v_cndmask_b32_e64 v20, v6, v14, s[4:5]
	v_pk_add_f32 v[0:1], v[242:243], v[0:1]
	s_nop 0
	v_mul_f32_e32 v8, 0xbfb8aa3b, v1
	v_exp_f32_e32 v8, v8
	v_mul_f32_e32 v9, 0xbfb8aa3b, v0
	v_mov_b32_dpp v14, v20 row_ror:1 row_mask:0xf bank_mask:0xf
	v_cndmask_b32_e64 v20, v2, v10, s[4:5]
	v_exp_f32_e32 v18, v9
	v_add_f32_e32 v8, 1.0, v8
	v_mov_b32_dpp v10, v20 row_ror:1 row_mask:0xf bank_mask:0xf
	v_rcp_f32_e32 v9, v8
	v_add_f32_e32 v8, 1.0, v18
	v_mov_b32_dpp v20, v21 row_ror:15 row_mask:0xf bank_mask:0xf
	v_cndmask_b32_e64 v21, v2, 0, s[6:7]
	v_rcp_f32_e32 v8, v8
	v_pk_add_f32 v[4:5], v[180:181], v[4:5]
	v_mov_b32_dpp v22, v21 row_ror:15 row_mask:0xf bank_mask:0xf
	v_cndmask_b32_e64 v21, v7, v15, s[4:5]
	v_pk_mul_f32 v[0:1], v[0:1], v[8:9]
	v_pk_mul_f32 v[6:7], v[6:7], v[248:249]
	v_mov_b32_dpp v15, v21 row_ror:1 row_mask:0xf bank_mask:0xf
	v_cndmask_b32_e64 v21, v3, v11, s[4:5]
	v_pk_mul_f32 v[2:3], v[2:3], v[236:237]
	v_pk_mul_f32 v[0:1], v[4:5], v[0:1]
	v_mov_b32_dpp v11, v21 row_ror:1 row_mask:0xf bank_mask:0xf
	v_pk_fma_f32 v[2:3], v[232:233], v[10:11], v[2:3]
	v_cvt_pk_bf16_f32 v0, v0, v1
	v_mov_b32_dpp v21, v23 row_ror:15 row_mask:0xf bank_mask:0xf
	v_pk_fma_f32 v[6:7], v[252:253], v[14:15], v[6:7]
	s_nop 0
	v_mov_b32_dpp v23, v24 row_ror:15 row_mask:0xf bank_mask:0xf
	v_pk_fma_f32 v[2:3], v[240:241], v[22:23], v[2:3]
	v_pk_fma_f32 v[6:7], v[192:193], v[20:21], v[6:7]
	v_pk_add_f32 v[2:3], v[244:245], v[2:3]
	v_pk_add_f32 v[6:7], v[182:183], v[6:7]
	v_mul_f32_e32 v4, 0xbfb8aa3b, v2
	v_exp_f32_e32 v4, v4
	v_mul_f32_e32 v5, 0xbfb8aa3b, v3
	v_exp_f32_e32 v5, v5
	v_add_f32_e32 v1, 1.0, v4
	v_rcp_f32_e32 v4, v1
	v_add_f32_e32 v1, 1.0, v5
	v_rcp_f32_e32 v5, v1
	s_nop 0
	v_pk_mul_f32 v[2:3], v[2:3], v[4:5]
	s_nop 0
	v_pk_mul_f32 v[2:3], v[6:7], v[2:3]
	s_nop 0
	v_cvt_pk_bf16_f32 v1, v2, v3
	global_store_dwordx2 v[104:105], v[0:1], off offset:32
	s_cbranch_vccnz .LBB0_1795
	s_andn2_b64 vcc, exec, s[2:3]
	s_cbranch_vccnz .LBB0_1794
	s_barrier
	s_branch .LBB0_1794
